# speedup vs baseline: 1.0163x; 1.0163x over previous
; #define STA(b, h, half, kt) STAGE(((b) * 2 + (h)) * G_HT * 2, pA, ((size_t)(half) * G_HALF * lda + (size_t)(kt) * G_BK) * 2, lda)
; #define STB(b, h, half, kt) STAGE((4 + (b) * 2 + (h)) * G_HT * 2, pB, ((size_t)(half) * G_HALF * K + (size_t)(kt) * G_BK) * 2, K)
; #define LDA(dst, b, h) for (int m = 0; m < 4; ++m) for (int k = 0; k < 2; ++k) \
;     dst[m][k] = *reinterpret_cast<const bf16x8*>(aRd + (((b) * 2 + (h)) * G_HT * 2 + m * 2048 + k * 1024))
; #define LDB(dst, b, h) for (int n = 0; n < 2; ++n) for (int k = 0; k < 2; ++k) \
;     dst[n][k] = *reinterpret_cast<const bf16x8*>(bRd + (((b) * 2 + (h)) * G_HT * 2 + n * 2048 + k * 1024))
; #define MMA(ai, bj, At, Bx) do { __builtin_amdgcn_s_setprio(1); \
;     for (int m = 0; m < 4; ++m) for (int n = 0; n < 2; ++n) for (int k = 0; k < 2; ++k) \
;       acc[ai][bj][m][n] = __builtin_amdgcn_mfma_f32_16x16x32_bf16(Bx[n][k], At[m][k], acc[ai][bj][m][n], 0, 0, 0);     \
;     __builtin_amdgcn_s_setprio(0); } while (0)
; #define WAIT_V(n) asm volatile("s_waitcnt vmcnt(" #n ")" ::: "memory")
; #define WAIT_L(n) asm volatile("s_waitcnt lgkmcnt(" #n ")" ::: "memory")
; #define BAR __builtin_amdgcn_s_barrier()
; #define SCHED __builtin_amdgcn_sched_barrier(0)
; template <int EPI>
; __device__ __forceinline__ void gemm_tile(const bf16* __restrict__ A, int lda, const bf16* __restrict__ Bt, int K,
;                                           int brow, int bcol, const EpiArgs& ea, char* shmc, bool has_next, int nbrow, int nbcol, bool first_tile) {
;     ...
;   for (int t = 0; t < nt - 2; t += 2) {
;     LDB(B0, 0, 0); SCHED; LDA(At, 0, 0); STA(1, 1, 1, t + 1);
;     WAIT_L(8); BAR; WAIT_L(0); MMA(0, 0, At, B0); BAR; SCHED;
;     LDB(B1, 0, 1); STB(0, 0, 0, t + 2);
;     BAR; WAIT_L(0); MMA(0, 1, At, B1); BAR;
;     LDA(At, 0, 1); STA(0, 0, 0, t + 2);
;     BAR; WAIT_L(0); MMA(1, 0, At, B0); BAR; SCHED;
;     STB(0, 1, 1, t + 2);
;     WAIT_V(6); BAR; MMA(1, 1, At, B1); BAR;
.LBB0_96:
	ds_read_b128 v[162:165], v141
	ds_read_b128 v[166:169], v142
	ds_read_b128 v[170:173], v143
	ds_read_b128 v[174:177], v144
	s_add_u32 s82, s34, 0xffffff00
	s_addc_u32 s83, s35, -1
	s_mov_b32 m0, s77
	ds_read_b128 v[178:181], v160
	ds_read_b128 v[182:185], v160 offset:1024
	ds_read_b128 v[186:189], v160 offset:2048
	ds_read_b128 v[190:193], v160 offset:3072
	ds_read_b128 v[194:197], v160 offset:4096
	ds_read_b128 v[198:201], v160 offset:5120
	ds_read_b128 v[202:205], v160 offset:6144
	ds_read_b128 v[206:209], v160 offset:7168
	v_lshl_add_u64 v[210:211], v[134:135], 0, s[82:83]
	global_load_lds_dwordx4 v[210:211], off
	v_lshl_add_u64 v[210:211], v[210:211], 0, s[0:1]
	s_mov_b32 m0, s68
	s_nop 0
	global_load_lds_dwordx4 v[210:211], off
	s_waitcnt lgkmcnt(8)
	s_barrier
	s_waitcnt lgkmcnt(0)
	v_mfma_f32_16x16x32_bf16 v[124:127], v[162:165], v[178:181], v[124:127]
	v_mfma_f32_16x16x32_bf16 v[120:123], v[170:173], v[178:181], v[120:123]
	v_mfma_f32_16x16x32_bf16 v[116:119], v[162:165], v[186:189], v[116:119]
	v_mfma_f32_16x16x32_bf16 v[112:115], v[170:173], v[186:189], v[112:115]
	v_mfma_f32_16x16x32_bf16 v[108:111], v[162:165], v[194:197], v[108:111]
	v_mfma_f32_16x16x32_bf16 v[104:107], v[170:173], v[194:197], v[104:107]
	v_mfma_f32_16x16x32_bf16 v[100:103], v[162:165], v[202:205], v[100:103]
	v_mfma_f32_16x16x32_bf16 v[96:99], v[170:173], v[202:205], v[96:99]
	v_mfma_f32_16x16x32_bf16 v[124:127], v[166:169], v[182:185], v[124:127]
	v_mfma_f32_16x16x32_bf16 v[120:123], v[174:177], v[182:185], v[120:123]
	v_mfma_f32_16x16x32_bf16 v[116:119], v[166:169], v[190:193], v[116:119]
	v_mfma_f32_16x16x32_bf16 v[112:115], v[174:177], v[190:193], v[112:115]
	v_mfma_f32_16x16x32_bf16 v[108:111], v[166:169], v[198:201], v[108:111]
	v_mfma_f32_16x16x32_bf16 v[104:107], v[174:177], v[198:201], v[104:107]
	v_mfma_f32_16x16x32_bf16 v[100:103], v[166:169], v[206:209], v[100:103]
	v_mfma_f32_16x16x32_bf16 v[96:99], v[174:177], v[206:209], v[96:99]
	s_barrier
	s_add_u32 s82, s34, 0xffefff80
	s_addc_u32 s83, s35, -1
	s_mov_b64 s[84:85], s[82:83]
	s_mov_b32 m0, s71
	ds_read_b128 v[210:213], v145
	ds_read_b128 v[214:217], v146
	ds_read_b128 v[218:221], v147
	ds_read_b128 v[222:225], v148
	v_lshl_add_u64 v[226:227], v[136:137], 0, s[84:85]
	global_load_lds_dwordx4 v[226:227], off
	v_lshl_add_u64 v[226:227], v[226:227], 0, s[0:1]
	s_mov_b32 m0, s72
	s_nop 0
	global_load_lds_dwordx4 v[226:227], off
	s_barrier
	s_waitcnt lgkmcnt(0)
	v_mfma_f32_16x16x32_bf16 v[92:95], v[210:213], v[178:181], v[92:95]
	v_mfma_f32_16x16x32_bf16 v[88:91], v[218:221], v[178:181], v[88:91]
	v_mfma_f32_16x16x32_bf16 v[84:87], v[210:213], v[186:189], v[84:87]
	v_mfma_f32_16x16x32_bf16 v[80:83], v[218:221], v[186:189], v[80:83]
	v_mfma_f32_16x16x32_bf16 v[76:79], v[210:213], v[194:197], v[76:79]
	v_mfma_f32_16x16x32_bf16 v[72:75], v[218:221], v[194:197], v[72:75]
	v_mfma_f32_16x16x32_bf16 v[68:71], v[210:213], v[202:205], v[68:71]
	v_mfma_f32_16x16x32_bf16 v[64:67], v[218:221], v[202:205], v[64:67]
	v_mfma_f32_16x16x32_bf16 v[92:95], v[214:217], v[182:185], v[92:95]
	v_mfma_f32_16x16x32_bf16 v[88:91], v[222:225], v[182:185], v[88:91]
	v_mfma_f32_16x16x32_bf16 v[84:87], v[214:217], v[190:193], v[84:87]
	v_mfma_f32_16x16x32_bf16 v[80:83], v[222:225], v[190:193], v[80:83]
	v_mfma_f32_16x16x32_bf16 v[76:79], v[214:217], v[198:201], v[76:79]
	v_mfma_f32_16x16x32_bf16 v[72:75], v[222:225], v[198:201], v[72:75]
	v_mfma_f32_16x16x32_bf16 v[68:71], v[214:217], v[206:209], v[68:71]
	v_mfma_f32_16x16x32_bf16 v[64:67], v[222:225], v[206:209], v[64:67]
	s_mov_b32 m0, s7
	s_barrier
	ds_read_b128 v[178:181], v160 offset:16384
	ds_read_b128 v[182:185], v160 offset:17408
	ds_read_b128 v[186:189], v160 offset:18432
	ds_read_b128 v[190:193], v160 offset:19456
	ds_read_b128 v[194:197], v160 offset:20480
	ds_read_b128 v[198:201], v160 offset:21504
	ds_read_b128 v[202:205], v160 offset:22528
	ds_read_b128 v[206:209], v160 offset:23552
	v_lshl_add_u64 v[226:227], v[134:135], 0, s[82:83]
	global_load_lds_dwordx4 v[226:227], off
	v_lshl_add_u64 v[226:227], v[226:227], 0, s[0:1]
	s_mov_b32 m0, s79
	s_nop 0
	global_load_lds_dwordx4 v[226:227], off
	s_barrier
	s_waitcnt lgkmcnt(0)
	v_mfma_f32_16x16x32_bf16 v[60:63], v[162:165], v[178:181], v[60:63]
	v_mfma_f32_16x16x32_bf16 v[56:59], v[170:173], v[178:181], v[56:59]
	v_mfma_f32_16x16x32_bf16 v[52:55], v[162:165], v[186:189], v[52:55]
	v_mfma_f32_16x16x32_bf16 v[48:51], v[170:173], v[186:189], v[48:51]
	v_mfma_f32_16x16x32_bf16 v[44:47], v[162:165], v[194:197], v[44:47]
	v_mfma_f32_16x16x32_bf16 v[40:43], v[170:173], v[194:197], v[40:43]
	v_mfma_f32_16x16x32_bf16 v[36:39], v[162:165], v[202:205], v[36:39]
	v_mfma_f32_16x16x32_bf16 v[32:35], v[170:173], v[202:205], v[32:35]
	v_mfma_f32_16x16x32_bf16 v[60:63], v[166:169], v[182:185], v[60:63]
	v_mfma_f32_16x16x32_bf16 v[56:59], v[174:177], v[182:185], v[56:59]
	v_mfma_f32_16x16x32_bf16 v[52:55], v[166:169], v[190:193], v[52:55]
	v_mfma_f32_16x16x32_bf16 v[48:51], v[174:177], v[190:193], v[48:51]
	v_mfma_f32_16x16x32_bf16 v[44:47], v[166:169], v[198:201], v[44:47]
	v_mfma_f32_16x16x32_bf16 v[40:43], v[174:177], v[198:201], v[40:43]
	v_mfma_f32_16x16x32_bf16 v[36:39], v[166:169], v[206:209], v[36:39]
	v_mfma_f32_16x16x32_bf16 v[32:35], v[174:177], v[206:209], v[32:35]
	s_barrier
	s_add_u32 s82, s34, 0xffffff80
	s_addc_u32 s83, s35, -1
	s_mov_b64 s[84:85], s[82:83]
	s_mov_b32 m0, s73
	v_lshl_add_u64 v[162:163], v[136:137], 0, s[84:85]
	global_load_lds_dwordx4 v[162:163], off
	v_lshl_add_u64 v[162:163], v[162:163], 0, s[0:1]
	s_mov_b32 m0, s74
	s_nop 0
	global_load_lds_dwordx4 v[162:163], off
	s_waitcnt vmcnt(6)
	s_barrier
; #define STA(b, h, half, kt) STAGE(((b) * 2 + (h)) * G_HT * 2, pA, ((size_t)(half) * G_HALF * lda + (size_t)(kt) * G_BK) * 2, lda)
; #define STB(b, h, half, kt) STAGE((4 + (b) * 2 + (h)) * G_HT * 2, pB, ((size_t)(half) * G_HALF * K + (size_t)(kt) * G_BK) * 2, K)
; #define LDA(dst, b, h) for (int m = 0; m < 4; ++m) for (int k = 0; k < 2; ++k) \
;     dst[m][k] = *reinterpret_cast<const bf16x8*>(aRd + (((b) * 2 + (h)) * G_HT * 2 + m * 2048 + k * 1024))
; #define LDB(dst, b, h) for (int n = 0; n < 2; ++n) for (int k = 0; k < 2; ++k) \
;     dst[n][k] = *reinterpret_cast<const bf16x8*>(bRd + (((b) * 2 + (h)) * G_HT * 2 + n * 2048 + k * 1024))
; #define MMA(ai, bj, At, Bx) do { __builtin_amdgcn_s_setprio(1); \
;     for (int m = 0; m < 4; ++m) for (int n = 0; n < 2; ++n) for (int k = 0; k < 2; ++k) \
;       acc[ai][bj][m][n] = __builtin_amdgcn_mfma_f32_16x16x32_bf16(Bx[n][k], At[m][k], acc[ai][bj][m][n], 0, 0, 0);     \
;     __builtin_amdgcn_s_setprio(0); } while (0)
; #define WAIT_V(n) asm volatile("s_waitcnt vmcnt(" #n ")" ::: "memory")
; #define WAIT_L(n) asm volatile("s_waitcnt lgkmcnt(" #n ")" ::: "memory")
; #define BAR __builtin_amdgcn_s_barrier()
; #define SCHED __builtin_amdgcn_sched_barrier(0)
; template <int EPI>
; __device__ __forceinline__ void gemm_tile(const bf16* __restrict__ A, int lda, const bf16* __restrict__ Bt, int K,
;                                           int brow, int bcol, const EpiArgs& ea, char* shmc, bool has_next, int nbrow, int nbcol, bool first_tile) {
;     ...
;     WAIT_V(6); BAR; MMA(1, 1, At, B1); BAR;
;     LDB(B0, 1, 0); SCHED; LDA(At, 1, 0); STA(0, 1, 1, t + 2);
;     WAIT_L(8); BAR; WAIT_L(0); MMA(0, 0, At, B0); BAR; SCHED;
;     LDB(B1, 1, 1); STB(1, 0, 0, t + 3);
;     BAR; WAIT_L(0); MMA(0, 1, At, B1); BAR;
;     LDA(At, 1, 1); STA(1, 0, 0, t + 3);
;     BAR; WAIT_L(0); MMA(1, 0, At, B0); BAR; SCHED;
	v_mfma_f32_16x16x32_bf16 v[28:31], v[210:213], v[178:181], v[28:31]
	v_mfma_f32_16x16x32_bf16 v[24:27], v[218:221], v[178:181], v[24:27]
	v_mfma_f32_16x16x32_bf16 v[20:23], v[210:213], v[186:189], v[20:23]
	v_mfma_f32_16x16x32_bf16 v[16:19], v[218:221], v[186:189], v[16:19]
	v_mfma_f32_16x16x32_bf16 v[12:15], v[210:213], v[194:197], v[12:15]
	v_mfma_f32_16x16x32_bf16 v[8:11], v[218:221], v[194:197], v[8:11]
	v_mfma_f32_16x16x32_bf16 v[4:7], v[210:213], v[202:205], v[4:7]
	v_mfma_f32_16x16x32_bf16 v[0:3], v[218:221], v[202:205], v[0:3]
	v_mfma_f32_16x16x32_bf16 v[28:31], v[214:217], v[182:185], v[28:31]
	v_mfma_f32_16x16x32_bf16 v[24:27], v[222:225], v[182:185], v[24:27]
	v_mfma_f32_16x16x32_bf16 v[20:23], v[214:217], v[190:193], v[20:23]
	v_mfma_f32_16x16x32_bf16 v[16:19], v[222:225], v[190:193], v[16:19]
	v_mfma_f32_16x16x32_bf16 v[12:15], v[214:217], v[198:201], v[12:15]
	v_mfma_f32_16x16x32_bf16 v[8:11], v[222:225], v[198:201], v[8:11]
	v_mfma_f32_16x16x32_bf16 v[4:7], v[214:217], v[206:209], v[4:7]
	v_mfma_f32_16x16x32_bf16 v[0:3], v[222:225], v[206:209], v[0:3]
	s_barrier
	ds_read_b128 v[162:165], v149
	ds_read_b128 v[166:169], v150
	ds_read_b128 v[170:173], v151
	ds_read_b128 v[174:177], v152
	s_mov_b32 m0, s80
	ds_read_b128 v[178:181], v160 offset:32768
	ds_read_b128 v[182:185], v160 offset:33792
	ds_read_b128 v[186:189], v160 offset:34816
	ds_read_b128 v[190:193], v160 offset:35840
	ds_read_b128 v[194:197], v160 offset:36864
	ds_read_b128 v[198:201], v160 offset:37888
	ds_read_b128 v[202:205], v160 offset:38912
	ds_read_b128 v[206:209], v160 offset:39936
	v_lshl_add_u64 v[210:211], v[134:135], 0, s[82:83]
	global_load_lds_dwordx4 v[210:211], off
	v_lshl_add_u64 v[210:211], v[210:211], 0, s[0:1]
	s_mov_b32 m0, s81
	s_nop 0
	global_load_lds_dwordx4 v[210:211], off
	s_waitcnt lgkmcnt(8)
	s_barrier
	s_waitcnt lgkmcnt(0)
	v_mfma_f32_16x16x32_bf16 v[124:127], v[162:165], v[178:181], v[124:127]
	v_mfma_f32_16x16x32_bf16 v[120:123], v[170:173], v[178:181], v[120:123]
	v_mfma_f32_16x16x32_bf16 v[116:119], v[162:165], v[186:189], v[116:119]
	v_mfma_f32_16x16x32_bf16 v[112:115], v[170:173], v[186:189], v[112:115]
	v_mfma_f32_16x16x32_bf16 v[108:111], v[162:165], v[194:197], v[108:111]
	v_mfma_f32_16x16x32_bf16 v[104:107], v[170:173], v[194:197], v[104:107]
	v_mfma_f32_16x16x32_bf16 v[100:103], v[162:165], v[202:205], v[100:103]
	v_mfma_f32_16x16x32_bf16 v[96:99], v[170:173], v[202:205], v[96:99]
	v_mfma_f32_16x16x32_bf16 v[124:127], v[166:169], v[182:185], v[124:127]
	v_mfma_f32_16x16x32_bf16 v[120:123], v[174:177], v[182:185], v[120:123]
	v_mfma_f32_16x16x32_bf16 v[116:119], v[166:169], v[190:193], v[116:119]
	v_mfma_f32_16x16x32_bf16 v[112:115], v[174:177], v[190:193], v[112:115]
	v_mfma_f32_16x16x32_bf16 v[108:111], v[166:169], v[198:201], v[108:111]
	v_mfma_f32_16x16x32_bf16 v[104:107], v[174:177], v[198:201], v[104:107]
	v_mfma_f32_16x16x32_bf16 v[100:103], v[166:169], v[206:209], v[100:103]
	v_mfma_f32_16x16x32_bf16 v[96:99], v[174:177], v[206:209], v[96:99]
	s_barrier
	s_add_u32 s82, s34, 0xfff00000
	s_addc_u32 s83, s35, -1
	s_mov_b64 s[84:85], s[82:83]
	s_mov_b32 m0, s11
	ds_read_b128 v[210:213], v153
	ds_read_b128 v[214:217], v154
	ds_read_b128 v[218:221], v155
	ds_read_b128 v[222:225], v156
	v_lshl_add_u64 v[226:227], v[136:137], 0, s[84:85]
	global_load_lds_dwordx4 v[226:227], off
	v_lshl_add_u64 v[226:227], v[226:227], 0, s[0:1]
	s_mov_b32 m0, s63
	s_nop 0
	global_load_lds_dwordx4 v[226:227], off
	s_barrier
	s_waitcnt lgkmcnt(0)
	v_mfma_f32_16x16x32_bf16 v[92:95], v[210:213], v[178:181], v[92:95]
	v_mfma_f32_16x16x32_bf16 v[88:91], v[218:221], v[178:181], v[88:91]
	v_mfma_f32_16x16x32_bf16 v[84:87], v[210:213], v[186:189], v[84:87]
	v_mfma_f32_16x16x32_bf16 v[80:83], v[218:221], v[186:189], v[80:83]
	v_mfma_f32_16x16x32_bf16 v[76:79], v[210:213], v[194:197], v[76:79]
	v_mfma_f32_16x16x32_bf16 v[72:75], v[218:221], v[194:197], v[72:75]
	v_mfma_f32_16x16x32_bf16 v[68:71], v[210:213], v[202:205], v[68:71]
	v_mfma_f32_16x16x32_bf16 v[64:67], v[218:221], v[202:205], v[64:67]
	v_mfma_f32_16x16x32_bf16 v[92:95], v[214:217], v[182:185], v[92:95]
	v_mfma_f32_16x16x32_bf16 v[88:91], v[222:225], v[182:185], v[88:91]
	v_mfma_f32_16x16x32_bf16 v[84:87], v[214:217], v[190:193], v[84:87]
	v_mfma_f32_16x16x32_bf16 v[80:83], v[222:225], v[190:193], v[80:83]
	v_mfma_f32_16x16x32_bf16 v[76:79], v[214:217], v[198:201], v[76:79]
	v_mfma_f32_16x16x32_bf16 v[72:75], v[222:225], v[198:201], v[72:75]
	v_mfma_f32_16x16x32_bf16 v[68:71], v[214:217], v[206:209], v[68:71]
	v_mfma_f32_16x16x32_bf16 v[64:67], v[222:225], v[206:209], v[64:67]
	s_mov_b32 m0, s66
	s_barrier
	ds_read_b128 v[178:181], v160 offset:49152
	ds_read_b128 v[182:185], v160 offset:50176
	ds_read_b128 v[186:189], v160 offset:51200
	ds_read_b128 v[190:193], v160 offset:52224
	ds_read_b128 v[194:197], v160 offset:53248
	ds_read_b128 v[198:201], v160 offset:54272
	ds_read_b128 v[202:205], v160 offset:55296
	ds_read_b128 v[206:209], v160 offset:56320
	v_lshl_add_u64 v[226:227], v[134:135], 0, s[82:83]
	global_load_lds_dwordx4 v[226:227], off
	v_lshl_add_u64 v[226:227], v[226:227], 0, s[0:1]
	s_mov_b32 m0, s67
	s_nop 0
	global_load_lds_dwordx4 v[226:227], off
	s_barrier
; #define STA(b, h, half, kt) STAGE(((b) * 2 + (h)) * G_HT * 2, pA, ((size_t)(half) * G_HALF * lda + (size_t)(kt) * G_BK) * 2, lda)
; #define STB(b, h, half, kt) STAGE((4 + (b) * 2 + (h)) * G_HT * 2, pB, ((size_t)(half) * G_HALF * K + (size_t)(kt) * G_BK) * 2, K)
; #define LDA(dst, b, h) for (int m = 0; m < 4; ++m) for (int k = 0; k < 2; ++k) \
;     dst[m][k] = *reinterpret_cast<const bf16x8*>(aRd + (((b) * 2 + (h)) * G_HT * 2 + m * 2048 + k * 1024))
; #define LDB(dst, b, h) for (int n = 0; n < 2; ++n) for (int k = 0; k < 2; ++k) \
;     dst[n][k] = *reinterpret_cast<const bf16x8*>(bRd + (((b) * 2 + (h)) * G_HT * 2 + n * 2048 + k * 1024))
; #define MMA(ai, bj, At, Bx) do { __builtin_amdgcn_s_setprio(1); \
;     for (int m = 0; m < 4; ++m) for (int n = 0; n < 2; ++n) for (int k = 0; k < 2; ++k) \
;       acc[ai][bj][m][n] = __builtin_amdgcn_mfma_f32_16x16x32_bf16(Bx[n][k], At[m][k], acc[ai][bj][m][n], 0, 0, 0);     \
;     __builtin_amdgcn_s_setprio(0); } while (0)
; #define WAIT_V(n) asm volatile("s_waitcnt vmcnt(" #n ")" ::: "memory")
; #define WAIT_L(n) asm volatile("s_waitcnt lgkmcnt(" #n ")" ::: "memory")
; #define BAR __builtin_amdgcn_s_barrier()
; #define SCHED __builtin_amdgcn_sched_barrier(0)
; template <int EPI>
; __device__ __forceinline__ void gemm_tile(const bf16* __restrict__ A, int lda, const bf16* __restrict__ Bt, int K,
;                                           int brow, int bcol, const EpiArgs& ea, char* shmc, bool has_next, int nbrow, int nbcol, bool first_tile) {
;     ...
;     BAR; WAIT_L(0); MMA(1, 0, At, B0); BAR; SCHED;
;     STB(1, 1, 1, t + 3);
;     WAIT_V(6); BAR; MMA(1, 1, At, B1); BAR;
;   }
;   { LDB(B0, 0, 0); LDA(At, 0, 0); STA(1, 1, 1, nt - 1);
;     BAR; WAIT_L(0); MMA(0, 0, At, B0); BAR;
;     LDB(B1, 0, 1); BAR; WAIT_L(0); MMA(0, 1, At, B1); BAR;
	s_waitcnt lgkmcnt(0)
	v_mfma_f32_16x16x32_bf16 v[60:63], v[162:165], v[178:181], v[60:63]
	v_mfma_f32_16x16x32_bf16 v[56:59], v[170:173], v[178:181], v[56:59]
	v_mfma_f32_16x16x32_bf16 v[52:55], v[162:165], v[186:189], v[52:55]
	v_mfma_f32_16x16x32_bf16 v[48:51], v[170:173], v[186:189], v[48:51]
	v_mfma_f32_16x16x32_bf16 v[44:47], v[162:165], v[194:197], v[44:47]
	v_mfma_f32_16x16x32_bf16 v[40:43], v[170:173], v[194:197], v[40:43]
	v_mfma_f32_16x16x32_bf16 v[36:39], v[162:165], v[202:205], v[36:39]
	v_mfma_f32_16x16x32_bf16 v[32:35], v[170:173], v[202:205], v[32:35]
	v_mfma_f32_16x16x32_bf16 v[60:63], v[166:169], v[182:185], v[60:63]
	v_mfma_f32_16x16x32_bf16 v[56:59], v[174:177], v[182:185], v[56:59]
	v_mfma_f32_16x16x32_bf16 v[52:55], v[166:169], v[190:193], v[52:55]
	v_mfma_f32_16x16x32_bf16 v[48:51], v[174:177], v[190:193], v[48:51]
	v_mfma_f32_16x16x32_bf16 v[44:47], v[166:169], v[198:201], v[44:47]
	v_mfma_f32_16x16x32_bf16 v[40:43], v[174:177], v[198:201], v[40:43]
	v_mfma_f32_16x16x32_bf16 v[36:39], v[166:169], v[206:209], v[36:39]
	v_mfma_f32_16x16x32_bf16 v[32:35], v[174:177], v[206:209], v[32:35]
	s_barrier
	s_mov_b64 s[82:83], s[34:35]
	s_mov_b32 m0, s69
	v_lshl_add_u64 v[162:163], v[136:137], 0, s[82:83]
	global_load_lds_dwordx4 v[162:163], off
	v_lshl_add_u64 v[162:163], v[162:163], 0, s[0:1]
	s_mov_b32 m0, s70
	s_nop 0
	global_load_lds_dwordx4 v[162:163], off
	s_waitcnt vmcnt(6)
	s_barrier
	v_mfma_f32_16x16x32_bf16 v[28:31], v[210:213], v[178:181], v[28:31]
	v_mfma_f32_16x16x32_bf16 v[24:27], v[218:221], v[178:181], v[24:27]
	v_mfma_f32_16x16x32_bf16 v[20:23], v[210:213], v[186:189], v[20:23]
	v_mfma_f32_16x16x32_bf16 v[16:19], v[218:221], v[186:189], v[16:19]
	v_mfma_f32_16x16x32_bf16 v[12:15], v[210:213], v[194:197], v[12:15]
	v_mfma_f32_16x16x32_bf16 v[8:11], v[218:221], v[194:197], v[8:11]
	v_mfma_f32_16x16x32_bf16 v[4:7], v[210:213], v[202:205], v[4:7]
	v_mfma_f32_16x16x32_bf16 v[0:3], v[218:221], v[202:205], v[0:3]
	v_mfma_f32_16x16x32_bf16 v[28:31], v[214:217], v[182:185], v[28:31]
	v_mfma_f32_16x16x32_bf16 v[24:27], v[222:225], v[182:185], v[24:27]
	v_mfma_f32_16x16x32_bf16 v[20:23], v[214:217], v[190:193], v[20:23]
	v_mfma_f32_16x16x32_bf16 v[16:19], v[222:225], v[190:193], v[16:19]
	v_mfma_f32_16x16x32_bf16 v[12:15], v[214:217], v[198:201], v[12:15]
	v_mfma_f32_16x16x32_bf16 v[8:11], v[222:225], v[198:201], v[8:11]
	v_mfma_f32_16x16x32_bf16 v[4:7], v[214:217], v[206:209], v[4:7]
	v_mfma_f32_16x16x32_bf16 v[0:3], v[222:225], v[206:209], v[0:3]
	s_add_i32 s75, s75, 2
	s_add_u32 s34, s34, 0x100
	s_addc_u32 s35, s35, 0
	s_cmp_lt_u32 s75, 60
	s_barrier
	s_cbranch_scc1 .LBB0_96
	s_mov_b64 s[34:35], 0x101f80
	s_mov_b32 m0, s77
	ds_read_b128 v[162:165], v141
	ds_read_b128 v[166:169], v142
	ds_read_b128 v[170:173], v143
	ds_read_b128 v[174:177], v144
	ds_read_b128 v[178:181], v160
	ds_read_b128 v[182:185], v160 offset:1024
	ds_read_b128 v[186:189], v160 offset:2048
	ds_read_b128 v[190:193], v160 offset:3072
	ds_read_b128 v[194:197], v160 offset:4096
	ds_read_b128 v[198:201], v160 offset:5120
	ds_read_b128 v[202:205], v160 offset:6144
	ds_read_b128 v[206:209], v160 offset:7168
	s_nop 0
	v_lshl_add_u64 v[134:135], v[134:135], 0, s[34:35]
	global_load_lds_dwordx4 v[134:135], off
	v_lshl_add_u64 v[134:135], v[134:135], 0, s[0:1]
	s_mov_b32 m0, s68
	s_nop 0
	global_load_lds_dwordx4 v[134:135], off
	s_barrier
	s_waitcnt lgkmcnt(0)
	s_setprio 1
	s_waitcnt lgkmcnt(0)
	v_mfma_f32_16x16x32_bf16 v[124:127], v[162:165], v[178:181], v[124:127]
	v_mfma_f32_16x16x32_bf16 v[116:119], v[162:165], v[186:189], v[116:119]
	v_mfma_f32_16x16x32_bf16 v[112:115], v[170:173], v[186:189], v[112:115]
	v_mfma_f32_16x16x32_bf16 v[100:103], v[162:165], v[202:205], v[100:103]
	v_mfma_f32_16x16x32_bf16 v[96:99], v[170:173], v[202:205], v[96:99]
	v_mfma_f32_16x16x32_bf16 v[124:127], v[166:169], v[182:185], v[124:127]
	v_mfma_f32_16x16x32_bf16 v[120:123], v[170:173], v[178:181], v[120:123]
	v_mfma_f32_16x16x32_bf16 v[116:119], v[166:169], v[190:193], v[116:119]
	v_mfma_f32_16x16x32_bf16 v[112:115], v[174:177], v[190:193], v[112:115]
	v_mfma_f32_16x16x32_bf16 v[108:111], v[162:165], v[194:197], v[108:111]
	v_mfma_f32_16x16x32_bf16 v[104:107], v[170:173], v[194:197], v[104:107]
	v_mfma_f32_16x16x32_bf16 v[100:103], v[166:169], v[206:209], v[100:103]
	v_mfma_f32_16x16x32_bf16 v[96:99], v[174:177], v[206:209], v[96:99]
	v_mfma_f32_16x16x32_bf16 v[134:137], v[174:177], v[182:185], v[120:123]
	v_mfma_f32_16x16x32_bf16 v[210:213], v[166:169], v[198:201], v[108:111]
	v_mfma_f32_16x16x32_bf16 v[214:217], v[174:177], v[198:201], v[104:107]
	s_setprio 0
	s_barrier
	s_nop 0
	ds_read_b128 v[104:107], v145
	ds_read_b128 v[108:111], v146
	ds_read_b128 v[120:123], v147
	ds_read_b128 v[218:221], v148
	s_barrier
	s_waitcnt lgkmcnt(0)
	s_setprio 1
	s_waitcnt lgkmcnt(0)
	v_mfma_f32_16x16x32_bf16 v[84:87], v[104:107], v[186:189], v[84:87]
	v_mfma_f32_16x16x32_bf16 v[80:83], v[120:123], v[186:189], v[80:83]
	v_mfma_f32_16x16x32_bf16 v[68:71], v[104:107], v[202:205], v[68:71]
	v_mfma_f32_16x16x32_bf16 v[92:95], v[104:107], v[178:181], v[92:95]
	v_mfma_f32_16x16x32_bf16 v[88:91], v[120:123], v[178:181], v[88:91]
	v_mfma_f32_16x16x32_bf16 v[84:87], v[108:111], v[190:193], v[84:87]
	v_mfma_f32_16x16x32_bf16 v[80:83], v[218:221], v[190:193], v[80:83]
	v_mfma_f32_16x16x32_bf16 v[76:79], v[104:107], v[194:197], v[76:79]
	v_mfma_f32_16x16x32_bf16 v[72:75], v[120:123], v[194:197], v[72:75]
	v_mfma_f32_16x16x32_bf16 v[68:71], v[108:111], v[206:209], v[68:71]
	v_mfma_f32_16x16x32_bf16 v[64:67], v[120:123], v[202:205], v[64:67]
	v_mfma_f32_16x16x32_bf16 v[222:225], v[108:111], v[182:185], v[92:95]
	v_mfma_f32_16x16x32_bf16 v[178:181], v[218:221], v[182:185], v[88:91]
	v_mfma_f32_16x16x32_bf16 v[182:185], v[108:111], v[198:201], v[76:79]
	v_mfma_f32_16x16x32_bf16 v[186:189], v[218:221], v[198:201], v[72:75]
	v_mfma_f32_16x16x32_bf16 v[190:193], v[218:221], v[206:209], v[64:67]
	s_setprio 0
	s_barrier
; #define LDA(dst, b, h) for (int m = 0; m < 4; ++m) for (int k = 0; k < 2; ++k) \
;     dst[m][k] = *reinterpret_cast<const bf16x8*>(aRd + (((b) * 2 + (h)) * G_HT * 2 + m * 2048 + k * 1024))
; #define LDB(dst, b, h) for (int n = 0; n < 2; ++n) for (int k = 0; k < 2; ++k) \
;     dst[n][k] = *reinterpret_cast<const bf16x8*>(bRd + (((b) * 2 + (h)) * G_HT * 2 + n * 2048 + k * 1024))
; #define MMA(ai, bj, At, Bx) do { __builtin_amdgcn_s_setprio(1); \
;     for (int m = 0; m < 4; ++m) for (int n = 0; n < 2; ++n) for (int k = 0; k < 2; ++k) \
;       acc[ai][bj][m][n] = __builtin_amdgcn_mfma_f32_16x16x32_bf16(Bx[n][k], At[m][k], acc[ai][bj][m][n], 0, 0, 0);     \
;     __builtin_amdgcn_s_setprio(0); } while (0)
; #define WAIT_V(n) asm volatile("s_waitcnt vmcnt(" #n ")" ::: "memory")
; #define WAIT_L(n) asm volatile("s_waitcnt lgkmcnt(" #n ")" ::: "memory")
; #define BAR __builtin_amdgcn_s_barrier()
; template <int EPI>
; __device__ __forceinline__ void gemm_tile(const bf16* __restrict__ A, int lda, const bf16* __restrict__ Bt, int K,
;                                           int brow, int bcol, const EpiArgs& ea, char* shmc, bool has_next, int nbrow, int nbcol, bool first_tile) {
;     ...
;     LDA(At, 0, 1); WAIT_V(4); BAR; WAIT_L(0); MMA(1, 0, At, B0); MMA(1, 1, At, B1); BAR; }
;   { LDB(B0, 1, 0); LDA(At, 1, 0); WAIT_V(2); BAR; WAIT_L(0); MMA(0, 0, At, B0); BAR;
	s_nop 0
	ds_read_b128 v[64:67], v160 offset:16384
	ds_read_b128 v[72:75], v160 offset:17408
	ds_read_b128 v[76:79], v160 offset:18432
	ds_read_b128 v[88:91], v160 offset:19456
	ds_read_b128 v[92:95], v160 offset:20480
	ds_read_b128 v[194:197], v160 offset:21504
	ds_read_b128 v[198:201], v160 offset:22528
	ds_read_b128 v[202:205], v160 offset:23552
	s_waitcnt vmcnt(4)
	s_barrier
	s_waitcnt lgkmcnt(0)
	s_setprio 1
	s_waitcnt lgkmcnt(0)
	v_mfma_f32_16x16x32_bf16 v[60:63], v[162:165], v[64:67], v[60:63]
	v_mfma_f32_16x16x32_bf16 v[52:55], v[162:165], v[76:79], v[52:55]
	v_mfma_f32_16x16x32_bf16 v[48:51], v[170:173], v[76:79], v[48:51]
	v_mfma_f32_16x16x32_bf16 v[36:39], v[162:165], v[198:201], v[36:39]
	v_mfma_f32_16x16x32_bf16 v[32:35], v[170:173], v[198:201], v[32:35]
	v_mfma_f32_16x16x32_bf16 v[60:63], v[166:169], v[72:75], v[60:63]
	v_mfma_f32_16x16x32_bf16 v[56:59], v[170:173], v[64:67], v[56:59]
	v_mfma_f32_16x16x32_bf16 v[52:55], v[166:169], v[88:91], v[52:55]
	v_mfma_f32_16x16x32_bf16 v[48:51], v[174:177], v[88:91], v[48:51]
	v_mfma_f32_16x16x32_bf16 v[44:47], v[162:165], v[92:95], v[44:47]
	v_mfma_f32_16x16x32_bf16 v[40:43], v[170:173], v[92:95], v[40:43]
	v_mfma_f32_16x16x32_bf16 v[36:39], v[166:169], v[202:205], v[36:39]
	v_mfma_f32_16x16x32_bf16 v[32:35], v[174:177], v[202:205], v[32:35]
	v_mfma_f32_16x16x32_bf16 v[206:209], v[174:177], v[72:75], v[56:59]
	v_mfma_f32_16x16x32_bf16 v[226:229], v[166:169], v[194:197], v[44:47]
	v_mfma_f32_16x16x32_bf16 v[230:233], v[174:177], v[194:197], v[40:43]
	s_setprio 0
	s_setprio 1
	v_mfma_f32_16x16x32_bf16 v[20:23], v[104:107], v[76:79], v[20:23]
	v_mfma_f32_16x16x32_bf16 v[16:19], v[120:123], v[76:79], v[16:19]
	v_mfma_f32_16x16x32_bf16 v[4:7], v[104:107], v[198:201], v[4:7]
	v_mfma_f32_16x16x32_bf16 v[28:31], v[104:107], v[64:67], v[28:31]
	v_mfma_f32_16x16x32_bf16 v[24:27], v[120:123], v[64:67], v[24:27]
	v_mfma_f32_16x16x32_bf16 v[20:23], v[108:111], v[88:91], v[20:23]
	v_mfma_f32_16x16x32_bf16 v[16:19], v[218:221], v[88:91], v[16:19]
	v_mfma_f32_16x16x32_bf16 v[12:15], v[104:107], v[92:95], v[12:15]
	v_mfma_f32_16x16x32_bf16 v[8:11], v[120:123], v[92:95], v[8:11]
	v_mfma_f32_16x16x32_bf16 v[4:7], v[108:111], v[202:205], v[4:7]
	v_mfma_f32_16x16x32_bf16 v[0:3], v[120:123], v[198:201], v[0:3]
	v_mfma_f32_16x16x32_bf16 v[162:165], v[108:111], v[72:75], v[28:31]
	v_mfma_f32_16x16x32_bf16 v[166:169], v[218:221], v[72:75], v[24:27]
	v_mfma_f32_16x16x32_bf16 v[170:173], v[108:111], v[194:197], v[12:15]
	v_mfma_f32_16x16x32_bf16 v[174:177], v[218:221], v[194:197], v[8:11]
	v_mfma_f32_16x16x32_bf16 v[194:197], v[218:221], v[202:205], v[0:3]
	s_setprio 0
	s_barrier
	s_nop 0
	ds_read_b128 v[0:3], v149
	ds_read_b128 v[8:11], v150
	ds_read_b128 v[12:15], v151
	ds_read_b128 v[198:201], v152
	ds_read_b128 v[24:27], v160 offset:32768
	ds_read_b128 v[28:31], v160 offset:33792
	ds_read_b128 v[40:43], v160 offset:34816
	ds_read_b128 v[44:47], v160 offset:35840
	ds_read_b128 v[56:59], v160 offset:36864
	ds_read_b128 v[64:67], v160 offset:37888
	ds_read_b128 v[202:205], v160 offset:38912
	ds_read_b128 v[218:221], v160 offset:39936
	s_waitcnt vmcnt(2)
	s_barrier
	s_waitcnt lgkmcnt(0)
	s_setprio 1
	s_waitcnt lgkmcnt(0)
	v_mfma_f32_16x16x32_bf16 v[72:75], v[0:3], v[24:27], v[124:127]
	v_mfma_f32_16x16x32_bf16 v[120:123], v[8:11], v[28:31], v[72:75]
	v_mfma_f32_16x16x32_bf16 v[72:75], v[12:15], v[24:27], v[134:137]
	v_mfma_f32_16x16x32_bf16 v[124:127], v[198:201], v[28:31], v[72:75]
	v_mfma_f32_16x16x32_bf16 v[72:75], v[0:3], v[40:43], v[116:119]
	v_mfma_f32_16x16x32_bf16 v[104:107], v[8:11], v[44:47], v[72:75]
	v_mfma_f32_16x16x32_bf16 v[72:75], v[12:15], v[40:43], v[112:115]
	v_mfma_f32_16x16x32_bf16 v[108:111], v[198:201], v[44:47], v[72:75]
	v_mfma_f32_16x16x32_bf16 v[72:75], v[0:3], v[56:59], v[210:213]
	v_mfma_f32_16x16x32_bf16 v[88:91], v[8:11], v[64:67], v[72:75]
	v_mfma_f32_16x16x32_bf16 v[72:75], v[12:15], v[56:59], v[214:217]
	v_mfma_f32_16x16x32_bf16 v[92:95], v[198:201], v[64:67], v[72:75]
	v_mfma_f32_16x16x32_bf16 v[72:75], v[0:3], v[202:205], v[100:103]
	v_mfma_f32_16x16x32_bf16 v[76:79], v[12:15], v[202:205], v[96:99]
	v_mfma_f32_16x16x32_bf16 v[72:75], v[8:11], v[218:221], v[72:75]
	v_mfma_f32_16x16x32_bf16 v[76:79], v[198:201], v[218:221], v[76:79]
	s_setprio 0
	s_barrier
; #define LDA(dst, b, h) for (int m = 0; m < 4; ++m) for (int k = 0; k < 2; ++k) \
;     dst[m][k] = *reinterpret_cast<const bf16x8*>(aRd + (((b) * 2 + (h)) * G_HT * 2 + m * 2048 + k * 1024))
; #define LDB(dst, b, h) for (int n = 0; n < 2; ++n) for (int k = 0; k < 2; ++k) \
;     dst[n][k] = *reinterpret_cast<const bf16x8*>(bRd + (((b) * 2 + (h)) * G_HT * 2 + n * 2048 + k * 1024))
; #define MMA(ai, bj, At, Bx) do { __builtin_amdgcn_s_setprio(1); \
;     for (int m = 0; m < 4; ++m) for (int n = 0; n < 2; ++n) for (int k = 0; k < 2; ++k) \
;       acc[ai][bj][m][n] = __builtin_amdgcn_mfma_f32_16x16x32_bf16(Bx[n][k], At[m][k], acc[ai][bj][m][n], 0, 0, 0);     \
;     __builtin_amdgcn_s_setprio(0); } while (0)
; #define WAIT_V(n) asm volatile("s_waitcnt vmcnt(" #n ")" ::: "memory")
; #define WAIT_L(n) asm volatile("s_waitcnt lgkmcnt(" #n ")" ::: "memory")
; #define BAR __builtin_amdgcn_s_barrier()
; template <int EPI>
; __device__ __forceinline__ void gemm_tile(const bf16* __restrict__ A, int lda, const bf16* __restrict__ Bt, int K,
;                                           int brow, int bcol, const EpiArgs& ea, char* shmc, bool has_next, int nbrow, int nbcol, bool first_tile) {
;     ...
;     LDB(B1, 1, 1); WAIT_V(0); BAR; WAIT_L(0); MMA(0, 1, At, B1); BAR;
;     LDA(At, 1, 1); BAR; WAIT_L(0); MMA(1, 0, At, B0); MMA(1, 1, At, B1); BAR; }
;   if (wr == 0) BAR;
	ds_read_b128 v[134:137], v153
	ds_read_b128 v[210:213], v154
	ds_read_b128 v[214:217], v155
	ds_read_b128 v[234:237], v156
	s_waitcnt vmcnt(0)
	s_barrier
	s_waitcnt lgkmcnt(0)
	s_setprio 1
	s_waitcnt lgkmcnt(0)
	v_mfma_f32_16x16x32_bf16 v[96:99], v[134:137], v[24:27], v[222:225]
	v_mfma_f32_16x16x32_bf16 v[24:27], v[214:217], v[24:27], v[178:181]
	v_mfma_f32_16x16x32_bf16 v[116:119], v[234:237], v[28:31], v[24:27]
	v_mfma_f32_16x16x32_bf16 v[24:27], v[134:137], v[40:43], v[84:87]
	v_mfma_f32_16x16x32_bf16 v[112:115], v[210:213], v[28:31], v[96:99]
	v_mfma_f32_16x16x32_bf16 v[96:99], v[210:213], v[44:47], v[24:27]
	v_mfma_f32_16x16x32_bf16 v[24:27], v[214:217], v[40:43], v[80:83]
	v_mfma_f32_16x16x32_bf16 v[100:103], v[234:237], v[44:47], v[24:27]
	v_mfma_f32_16x16x32_bf16 v[24:27], v[134:137], v[56:59], v[182:185]
	v_mfma_f32_16x16x32_bf16 v[80:83], v[210:213], v[64:67], v[24:27]
	v_mfma_f32_16x16x32_bf16 v[24:27], v[214:217], v[56:59], v[186:189]
	v_mfma_f32_16x16x32_bf16 v[84:87], v[234:237], v[64:67], v[24:27]
	v_mfma_f32_16x16x32_bf16 v[24:27], v[134:137], v[202:205], v[68:71]
	v_mfma_f32_16x16x32_bf16 v[64:67], v[210:213], v[218:221], v[24:27]
	v_mfma_f32_16x16x32_bf16 v[24:27], v[214:217], v[202:205], v[190:193]
	v_mfma_f32_16x16x32_bf16 v[68:71], v[234:237], v[218:221], v[24:27]
	s_setprio 0
	s_barrier
	ds_read_b128 v[178:181], v160 offset:49152
	ds_read_b128 v[182:185], v160 offset:50176
	ds_read_b128 v[186:189], v160 offset:51200
	ds_read_b128 v[190:193], v160 offset:52224
	ds_read_b128 v[202:205], v160 offset:53248
	ds_read_b128 v[218:221], v160 offset:54272
	ds_read_b128 v[222:225], v160 offset:55296
	ds_read_b128 v[238:241], v160 offset:56320
	s_barrier
	s_waitcnt lgkmcnt(0)
	s_setprio 1
	s_waitcnt lgkmcnt(0)
	v_mfma_f32_16x16x32_bf16 v[24:27], v[0:3], v[178:181], v[60:63]
	v_mfma_f32_16x16x32_bf16 v[56:59], v[8:11], v[182:185], v[24:27]
	v_mfma_f32_16x16x32_bf16 v[24:27], v[12:15], v[178:181], v[206:209]
	v_mfma_f32_16x16x32_bf16 v[60:63], v[198:201], v[182:185], v[24:27]
	v_mfma_f32_16x16x32_bf16 v[24:27], v[0:3], v[186:189], v[52:55]
	v_mfma_f32_16x16x32_bf16 v[40:43], v[8:11], v[190:193], v[24:27]
	v_mfma_f32_16x16x32_bf16 v[24:27], v[12:15], v[186:189], v[48:51]
	v_mfma_f32_16x16x32_bf16 v[44:47], v[198:201], v[190:193], v[24:27]
	v_mfma_f32_16x16x32_bf16 v[24:27], v[0:3], v[202:205], v[226:229]
	v_mfma_f32_16x16x32_bf16 v[0:3], v[0:3], v[222:225], v[36:39]
	v_mfma_f32_16x16x32_bf16 v[24:27], v[8:11], v[218:221], v[24:27]
	v_mfma_f32_16x16x32_bf16 v[28:31], v[12:15], v[202:205], v[230:233]
	v_mfma_f32_16x16x32_bf16 v[8:11], v[8:11], v[238:241], v[0:3]
	v_mfma_f32_16x16x32_bf16 v[0:3], v[12:15], v[222:225], v[32:35]
	v_mfma_f32_16x16x32_bf16 v[28:31], v[198:201], v[218:221], v[28:31]
	v_mfma_f32_16x16x32_bf16 v[12:15], v[198:201], v[238:241], v[0:3]
	s_setprio 0
	s_setprio 1
	v_mfma_f32_16x16x32_bf16 v[0:3], v[134:137], v[178:181], v[162:165]
	v_mfma_f32_16x16x32_bf16 v[48:51], v[210:213], v[182:185], v[0:3]
	v_mfma_f32_16x16x32_bf16 v[0:3], v[214:217], v[178:181], v[166:169]
	v_mfma_f32_16x16x32_bf16 v[52:55], v[234:237], v[182:185], v[0:3]
	v_mfma_f32_16x16x32_bf16 v[0:3], v[134:137], v[186:189], v[20:23]
	v_mfma_f32_16x16x32_bf16 v[32:35], v[210:213], v[190:193], v[0:3]
	v_mfma_f32_16x16x32_bf16 v[0:3], v[214:217], v[186:189], v[16:19]
	v_mfma_f32_16x16x32_bf16 v[36:39], v[234:237], v[190:193], v[0:3]
	v_mfma_f32_16x16x32_bf16 v[0:3], v[134:137], v[202:205], v[170:173]
	v_mfma_f32_16x16x32_bf16 v[16:19], v[210:213], v[218:221], v[0:3]
	v_mfma_f32_16x16x32_bf16 v[0:3], v[214:217], v[202:205], v[174:177]
	v_mfma_f32_16x16x32_bf16 v[20:23], v[234:237], v[218:221], v[0:3]
	v_mfma_f32_16x16x32_bf16 v[0:3], v[134:137], v[222:225], v[4:7]
	v_mfma_f32_16x16x32_bf16 v[4:7], v[214:217], v[222:225], v[194:197]
	v_mfma_f32_16x16x32_bf16 v[0:3], v[210:213], v[238:241], v[0:3]
	v_mfma_f32_16x16x32_bf16 v[4:7], v[234:237], v[238:241], v[4:7]
	s_setprio 0
	s_barrier
	s_and_saveexec_b64 s[34:35], s[4:5]
	s_cbranch_execz .LBB0_99
	s_barrier

; #define STA(b, h, half, kt) STAGE(((b) * 2 + (h)) * G_HT * 2, pA, ((size_t)(half) * G_HALF * lda + (size_t)(kt) * G_BK) * 2, lda)
; #define STB(b, h, half, kt) STAGE((4 + (b) * 2 + (h)) * G_HT * 2, pB, ((size_t)(half) * G_HALF * K + (size_t)(kt) * G_BK) * 2, K)
; #define LDA(dst, b, h) for (int m = 0; m < 4; ++m) for (int k = 0; k < 2; ++k) \
;     dst[m][k] = *reinterpret_cast<const bf16x8*>(aRd + (((b) * 2 + (h)) * G_HT * 2 + m * 2048 + k * 1024))
; #define LDB(dst, b, h) for (int n = 0; n < 2; ++n) for (int k = 0; k < 2; ++k) \
;     dst[n][k] = *reinterpret_cast<const bf16x8*>(bRd + (((b) * 2 + (h)) * G_HT * 2 + n * 2048 + k * 1024))
; #define MMA(ai, bj, At, Bx) do { __builtin_amdgcn_s_setprio(1); \
;     for (int m = 0; m < 4; ++m) for (int n = 0; n < 2; ++n) for (int k = 0; k < 2; ++k) \
;       acc[ai][bj][m][n] = __builtin_amdgcn_mfma_f32_16x16x32_bf16(Bx[n][k], At[m][k], acc[ai][bj][m][n], 0, 0, 0);     \
;     __builtin_amdgcn_s_setprio(0); } while (0)
; #define WAIT_V(n) asm volatile("s_waitcnt vmcnt(" #n ")" ::: "memory")
; #define WAIT_L(n) asm volatile("s_waitcnt lgkmcnt(" #n ")" ::: "memory")
; #define BAR __builtin_amdgcn_s_barrier()
; #define SCHED __builtin_amdgcn_sched_barrier(0)
; template <int EPI>
; __device__ __forceinline__ void gemm_tile(const bf16* __restrict__ A, int lda, const bf16* __restrict__ Bt, int K,
;                                           int brow, int bcol, const EpiArgs& ea, char* shmc, bool has_next, int nbrow, int nbcol, bool first_tile) {
;     ...
;   for (int t = 0; t < nt - 2; t += 2) {
;     LDB(B0, 0, 0); SCHED; LDA(At, 0, 0); STA(1, 1, 1, t + 1);
;     WAIT_L(8); BAR; WAIT_L(0); MMA(0, 0, At, B0); BAR; SCHED;
;     LDB(B1, 0, 1); STB(0, 0, 0, t + 2);
;     BAR; WAIT_L(0); MMA(0, 1, At, B1); BAR;
;     LDA(At, 0, 1); STA(0, 0, 0, t + 2);
;     BAR; WAIT_L(0); MMA(1, 0, At, B0); BAR; SCHED;
;     STB(0, 1, 1, t + 2);
;     WAIT_V(6); BAR; MMA(1, 1, At, B1); BAR;
.LBB0_654:
	ds_read_b128 v[140:143], v145
	ds_read_b128 v[166:169], v146
	ds_read_b128 v[170:173], v147
	ds_read_b128 v[174:177], v148
	s_add_u32 s42, s14, 0xffffff00
	s_addc_u32 s43, s15, -1
	s_mov_b32 m0, s29
	ds_read_b128 v[178:181], v164
	ds_read_b128 v[182:185], v164 offset:1024
	ds_read_b128 v[186:189], v164 offset:2048
	ds_read_b128 v[190:193], v164 offset:3072
	ds_read_b128 v[194:197], v164 offset:4096
	ds_read_b128 v[198:201], v164 offset:5120
	ds_read_b128 v[202:205], v164 offset:6144
	ds_read_b128 v[206:209], v164 offset:7168
	v_lshl_add_u64 v[210:211], v[136:137], 0, s[42:43]
	global_load_lds_dwordx4 v[210:211], off
	v_lshl_add_u64 v[210:211], v[210:211], 0, s[10:11]
	s_mov_b32 m0, s21
	s_nop 0
	global_load_lds_dwordx4 v[210:211], off
	s_waitcnt lgkmcnt(8)
	s_barrier
	s_waitcnt lgkmcnt(0)
	v_mfma_f32_16x16x32_bf16 v[124:127], v[140:143], v[178:181], v[124:127]
	v_mfma_f32_16x16x32_bf16 v[120:123], v[170:173], v[178:181], v[120:123]
	v_mfma_f32_16x16x32_bf16 v[116:119], v[140:143], v[186:189], v[116:119]
	v_mfma_f32_16x16x32_bf16 v[112:115], v[170:173], v[186:189], v[112:115]
	v_mfma_f32_16x16x32_bf16 v[108:111], v[140:143], v[194:197], v[108:111]
	v_mfma_f32_16x16x32_bf16 v[104:107], v[170:173], v[194:197], v[104:107]
	v_mfma_f32_16x16x32_bf16 v[100:103], v[140:143], v[202:205], v[100:103]
	v_mfma_f32_16x16x32_bf16 v[96:99], v[170:173], v[202:205], v[96:99]
	v_mfma_f32_16x16x32_bf16 v[124:127], v[166:169], v[182:185], v[124:127]
	v_mfma_f32_16x16x32_bf16 v[120:123], v[174:177], v[182:185], v[120:123]
	v_mfma_f32_16x16x32_bf16 v[116:119], v[166:169], v[190:193], v[116:119]
	v_mfma_f32_16x16x32_bf16 v[112:115], v[174:177], v[190:193], v[112:115]
	v_mfma_f32_16x16x32_bf16 v[108:111], v[166:169], v[198:201], v[108:111]
	v_mfma_f32_16x16x32_bf16 v[104:107], v[174:177], v[198:201], v[104:107]
	v_mfma_f32_16x16x32_bf16 v[100:103], v[166:169], v[206:209], v[100:103]
	v_mfma_f32_16x16x32_bf16 v[96:99], v[174:177], v[206:209], v[96:99]
	s_barrier
	s_add_u32 s42, s14, 0xffefff80
	s_addc_u32 s43, s15, -1
	s_mov_b64 s[48:49], s[42:43]
	s_mov_b32 m0, s24
	ds_read_b128 v[210:213], v149
	ds_read_b128 v[214:217], v150
	ds_read_b128 v[218:221], v151
	ds_read_b128 v[222:225], v152
	v_lshl_add_u64 v[226:227], v[138:139], 0, s[48:49]
	global_load_lds_dwordx4 v[226:227], off
	v_lshl_add_u64 v[226:227], v[226:227], 0, s[10:11]
	s_mov_b32 m0, s25
	s_nop 0
	global_load_lds_dwordx4 v[226:227], off
	s_barrier
	s_waitcnt lgkmcnt(0)
	v_mfma_f32_16x16x32_bf16 v[92:95], v[210:213], v[178:181], v[92:95]
	v_mfma_f32_16x16x32_bf16 v[88:91], v[218:221], v[178:181], v[88:91]
	v_mfma_f32_16x16x32_bf16 v[84:87], v[210:213], v[186:189], v[84:87]
	v_mfma_f32_16x16x32_bf16 v[80:83], v[218:221], v[186:189], v[80:83]
	v_mfma_f32_16x16x32_bf16 v[76:79], v[210:213], v[194:197], v[76:79]
	v_mfma_f32_16x16x32_bf16 v[72:75], v[218:221], v[194:197], v[72:75]
	v_mfma_f32_16x16x32_bf16 v[68:71], v[210:213], v[202:205], v[68:71]
	v_mfma_f32_16x16x32_bf16 v[64:67], v[218:221], v[202:205], v[64:67]
	v_mfma_f32_16x16x32_bf16 v[92:95], v[214:217], v[182:185], v[92:95]
	v_mfma_f32_16x16x32_bf16 v[88:91], v[222:225], v[182:185], v[88:91]
	v_mfma_f32_16x16x32_bf16 v[84:87], v[214:217], v[190:193], v[84:87]
	v_mfma_f32_16x16x32_bf16 v[80:83], v[222:225], v[190:193], v[80:83]
	v_mfma_f32_16x16x32_bf16 v[76:79], v[214:217], v[198:201], v[76:79]
	v_mfma_f32_16x16x32_bf16 v[72:75], v[222:225], v[198:201], v[72:75]
	v_mfma_f32_16x16x32_bf16 v[68:71], v[214:217], v[206:209], v[68:71]
	v_mfma_f32_16x16x32_bf16 v[64:67], v[222:225], v[206:209], v[64:67]
	s_mov_b32 m0, s1
	s_barrier
	ds_read_b128 v[178:181], v164 offset:16384
	ds_read_b128 v[182:185], v164 offset:17408
	ds_read_b128 v[186:189], v164 offset:18432
	ds_read_b128 v[190:193], v164 offset:19456
	ds_read_b128 v[194:197], v164 offset:20480
	ds_read_b128 v[198:201], v164 offset:21504
	ds_read_b128 v[202:205], v164 offset:22528
	ds_read_b128 v[206:209], v164 offset:23552
	v_lshl_add_u64 v[226:227], v[136:137], 0, s[42:43]
	global_load_lds_dwordx4 v[226:227], off
	v_lshl_add_u64 v[226:227], v[226:227], 0, s[10:11]
	s_mov_b32 m0, s30
	s_nop 0
	global_load_lds_dwordx4 v[226:227], off
	s_barrier
	s_waitcnt lgkmcnt(0)
	v_mfma_f32_16x16x32_bf16 v[60:63], v[140:143], v[178:181], v[60:63]
	v_mfma_f32_16x16x32_bf16 v[56:59], v[170:173], v[178:181], v[56:59]
	v_mfma_f32_16x16x32_bf16 v[52:55], v[140:143], v[186:189], v[52:55]
	v_mfma_f32_16x16x32_bf16 v[48:51], v[170:173], v[186:189], v[48:51]
	v_mfma_f32_16x16x32_bf16 v[44:47], v[140:143], v[194:197], v[44:47]
	v_mfma_f32_16x16x32_bf16 v[40:43], v[170:173], v[194:197], v[40:43]
	v_mfma_f32_16x16x32_bf16 v[36:39], v[140:143], v[202:205], v[36:39]
	v_mfma_f32_16x16x32_bf16 v[32:35], v[170:173], v[202:205], v[32:35]
	v_mfma_f32_16x16x32_bf16 v[60:63], v[166:169], v[182:185], v[60:63]
	v_mfma_f32_16x16x32_bf16 v[56:59], v[174:177], v[182:185], v[56:59]
	v_mfma_f32_16x16x32_bf16 v[52:55], v[166:169], v[190:193], v[52:55]
	v_mfma_f32_16x16x32_bf16 v[48:51], v[174:177], v[190:193], v[48:51]
	v_mfma_f32_16x16x32_bf16 v[44:47], v[166:169], v[198:201], v[44:47]
	v_mfma_f32_16x16x32_bf16 v[40:43], v[174:177], v[198:201], v[40:43]
	v_mfma_f32_16x16x32_bf16 v[36:39], v[166:169], v[206:209], v[36:39]
	v_mfma_f32_16x16x32_bf16 v[32:35], v[174:177], v[206:209], v[32:35]
	s_barrier
	s_add_u32 s42, s14, 0xffffff80
	s_addc_u32 s43, s15, -1
	s_mov_b64 s[48:49], s[42:43]
	s_mov_b32 m0, s26
	v_lshl_add_u64 v[140:141], v[138:139], 0, s[48:49]
	global_load_lds_dwordx4 v[140:141], off
	v_lshl_add_u64 v[140:141], v[140:141], 0, s[10:11]
	s_mov_b32 m0, s27
	s_nop 0
	global_load_lds_dwordx4 v[140:141], off
	s_waitcnt vmcnt(6)
	s_barrier
; #define STA(b, h, half, kt) STAGE(((b) * 2 + (h)) * G_HT * 2, pA, ((size_t)(half) * G_HALF * lda + (size_t)(kt) * G_BK) * 2, lda)
; #define STB(b, h, half, kt) STAGE((4 + (b) * 2 + (h)) * G_HT * 2, pB, ((size_t)(half) * G_HALF * K + (size_t)(kt) * G_BK) * 2, K)
; #define LDA(dst, b, h) for (int m = 0; m < 4; ++m) for (int k = 0; k < 2; ++k) \
;     dst[m][k] = *reinterpret_cast<const bf16x8*>(aRd + (((b) * 2 + (h)) * G_HT * 2 + m * 2048 + k * 1024))
; #define LDB(dst, b, h) for (int n = 0; n < 2; ++n) for (int k = 0; k < 2; ++k) \
;     dst[n][k] = *reinterpret_cast<const bf16x8*>(bRd + (((b) * 2 + (h)) * G_HT * 2 + n * 2048 + k * 1024))
; #define MMA(ai, bj, At, Bx) do { __builtin_amdgcn_s_setprio(1); \
;     for (int m = 0; m < 4; ++m) for (int n = 0; n < 2; ++n) for (int k = 0; k < 2; ++k) \
;       acc[ai][bj][m][n] = __builtin_amdgcn_mfma_f32_16x16x32_bf16(Bx[n][k], At[m][k], acc[ai][bj][m][n], 0, 0, 0);     \
;     __builtin_amdgcn_s_setprio(0); } while (0)
; #define WAIT_V(n) asm volatile("s_waitcnt vmcnt(" #n ")" ::: "memory")
; #define WAIT_L(n) asm volatile("s_waitcnt lgkmcnt(" #n ")" ::: "memory")
; #define BAR __builtin_amdgcn_s_barrier()
; #define SCHED __builtin_amdgcn_sched_barrier(0)
; template <int EPI>
; __device__ __forceinline__ void gemm_tile(const bf16* __restrict__ A, int lda, const bf16* __restrict__ Bt, int K,
;                                           int brow, int bcol, const EpiArgs& ea, char* shmc, bool has_next, int nbrow, int nbcol, bool first_tile) {
;     ...
;     WAIT_V(6); BAR; MMA(1, 1, At, B1); BAR;
;     LDB(B0, 1, 0); SCHED; LDA(At, 1, 0); STA(0, 1, 1, t + 2);
;     WAIT_L(8); BAR; WAIT_L(0); MMA(0, 0, At, B0); BAR; SCHED;
;     LDB(B1, 1, 1); STB(1, 0, 0, t + 3);
;     BAR; WAIT_L(0); MMA(0, 1, At, B1); BAR;
;     LDA(At, 1, 1); STA(1, 0, 0, t + 3);
;     BAR; WAIT_L(0); MMA(1, 0, At, B0); BAR; SCHED;
	v_mfma_f32_16x16x32_bf16 v[28:31], v[210:213], v[178:181], v[28:31]
	v_mfma_f32_16x16x32_bf16 v[24:27], v[218:221], v[178:181], v[24:27]
	v_mfma_f32_16x16x32_bf16 v[20:23], v[210:213], v[186:189], v[20:23]
	v_mfma_f32_16x16x32_bf16 v[16:19], v[218:221], v[186:189], v[16:19]
	v_mfma_f32_16x16x32_bf16 v[12:15], v[210:213], v[194:197], v[12:15]
	v_mfma_f32_16x16x32_bf16 v[8:11], v[218:221], v[194:197], v[8:11]
	v_mfma_f32_16x16x32_bf16 v[4:7], v[210:213], v[202:205], v[4:7]
	v_mfma_f32_16x16x32_bf16 v[0:3], v[218:221], v[202:205], v[0:3]
	v_mfma_f32_16x16x32_bf16 v[28:31], v[214:217], v[182:185], v[28:31]
	v_mfma_f32_16x16x32_bf16 v[24:27], v[222:225], v[182:185], v[24:27]
	v_mfma_f32_16x16x32_bf16 v[20:23], v[214:217], v[190:193], v[20:23]
	v_mfma_f32_16x16x32_bf16 v[16:19], v[222:225], v[190:193], v[16:19]
	v_mfma_f32_16x16x32_bf16 v[12:15], v[214:217], v[198:201], v[12:15]
	v_mfma_f32_16x16x32_bf16 v[8:11], v[222:225], v[198:201], v[8:11]
	v_mfma_f32_16x16x32_bf16 v[4:7], v[214:217], v[206:209], v[4:7]
	v_mfma_f32_16x16x32_bf16 v[0:3], v[222:225], v[206:209], v[0:3]
	s_barrier
	ds_read_b128 v[140:143], v153
	ds_read_b128 v[166:169], v154
	ds_read_b128 v[170:173], v155
	ds_read_b128 v[174:177], v156
	s_mov_b32 m0, s31
	ds_read_b128 v[178:181], v164 offset:32768
	ds_read_b128 v[182:185], v164 offset:33792
	ds_read_b128 v[186:189], v164 offset:34816
	ds_read_b128 v[190:193], v164 offset:35840
	ds_read_b128 v[194:197], v164 offset:36864
	ds_read_b128 v[198:201], v164 offset:37888
	ds_read_b128 v[202:205], v164 offset:38912
	ds_read_b128 v[206:209], v164 offset:39936
	v_lshl_add_u64 v[210:211], v[136:137], 0, s[42:43]
	global_load_lds_dwordx4 v[210:211], off
	v_lshl_add_u64 v[210:211], v[210:211], 0, s[10:11]
	s_mov_b32 m0, s34
	s_nop 0
	global_load_lds_dwordx4 v[210:211], off
	s_waitcnt lgkmcnt(8)
	s_barrier
	s_waitcnt lgkmcnt(0)
	v_mfma_f32_16x16x32_bf16 v[124:127], v[140:143], v[178:181], v[124:127]
	v_mfma_f32_16x16x32_bf16 v[120:123], v[170:173], v[178:181], v[120:123]
	v_mfma_f32_16x16x32_bf16 v[116:119], v[140:143], v[186:189], v[116:119]
	v_mfma_f32_16x16x32_bf16 v[112:115], v[170:173], v[186:189], v[112:115]
	v_mfma_f32_16x16x32_bf16 v[108:111], v[140:143], v[194:197], v[108:111]
	v_mfma_f32_16x16x32_bf16 v[104:107], v[170:173], v[194:197], v[104:107]
	v_mfma_f32_16x16x32_bf16 v[100:103], v[140:143], v[202:205], v[100:103]
	v_mfma_f32_16x16x32_bf16 v[96:99], v[170:173], v[202:205], v[96:99]
	v_mfma_f32_16x16x32_bf16 v[124:127], v[166:169], v[182:185], v[124:127]
	v_mfma_f32_16x16x32_bf16 v[120:123], v[174:177], v[182:185], v[120:123]
	v_mfma_f32_16x16x32_bf16 v[116:119], v[166:169], v[190:193], v[116:119]
	v_mfma_f32_16x16x32_bf16 v[112:115], v[174:177], v[190:193], v[112:115]
	v_mfma_f32_16x16x32_bf16 v[108:111], v[166:169], v[198:201], v[108:111]
	v_mfma_f32_16x16x32_bf16 v[104:107], v[174:177], v[198:201], v[104:107]
	v_mfma_f32_16x16x32_bf16 v[100:103], v[166:169], v[206:209], v[100:103]
	v_mfma_f32_16x16x32_bf16 v[96:99], v[174:177], v[206:209], v[96:99]
	s_barrier
	s_add_u32 s42, s14, 0xfff00000
	s_addc_u32 s43, s15, -1
	s_mov_b64 s[48:49], s[42:43]
	s_mov_b32 m0, s13
	ds_read_b128 v[210:213], v158
	ds_read_b128 v[214:217], v159
	ds_read_b128 v[218:221], v160
	ds_read_b128 v[222:225], v161
	v_lshl_add_u64 v[226:227], v[138:139], 0, s[48:49]
	global_load_lds_dwordx4 v[226:227], off
	v_lshl_add_u64 v[226:227], v[226:227], 0, s[10:11]
	s_mov_b32 m0, s18
	s_nop 0
	global_load_lds_dwordx4 v[226:227], off
	s_barrier
	s_waitcnt lgkmcnt(0)
	v_mfma_f32_16x16x32_bf16 v[92:95], v[210:213], v[178:181], v[92:95]
	v_mfma_f32_16x16x32_bf16 v[88:91], v[218:221], v[178:181], v[88:91]
	v_mfma_f32_16x16x32_bf16 v[84:87], v[210:213], v[186:189], v[84:87]
	v_mfma_f32_16x16x32_bf16 v[80:83], v[218:221], v[186:189], v[80:83]
	v_mfma_f32_16x16x32_bf16 v[76:79], v[210:213], v[194:197], v[76:79]
	v_mfma_f32_16x16x32_bf16 v[72:75], v[218:221], v[194:197], v[72:75]
	v_mfma_f32_16x16x32_bf16 v[68:71], v[210:213], v[202:205], v[68:71]
	v_mfma_f32_16x16x32_bf16 v[64:67], v[218:221], v[202:205], v[64:67]
	v_mfma_f32_16x16x32_bf16 v[92:95], v[214:217], v[182:185], v[92:95]
	v_mfma_f32_16x16x32_bf16 v[88:91], v[222:225], v[182:185], v[88:91]
	v_mfma_f32_16x16x32_bf16 v[84:87], v[214:217], v[190:193], v[84:87]
	v_mfma_f32_16x16x32_bf16 v[80:83], v[222:225], v[190:193], v[80:83]
	v_mfma_f32_16x16x32_bf16 v[76:79], v[214:217], v[198:201], v[76:79]
	v_mfma_f32_16x16x32_bf16 v[72:75], v[222:225], v[198:201], v[72:75]
	v_mfma_f32_16x16x32_bf16 v[68:71], v[214:217], v[206:209], v[68:71]
	v_mfma_f32_16x16x32_bf16 v[64:67], v[222:225], v[206:209], v[64:67]
	s_mov_b32 m0, s19
	s_barrier
	ds_read_b128 v[178:181], v164 offset:49152
	ds_read_b128 v[182:185], v164 offset:50176
	ds_read_b128 v[186:189], v164 offset:51200
	ds_read_b128 v[190:193], v164 offset:52224
	ds_read_b128 v[194:197], v164 offset:53248
	ds_read_b128 v[198:201], v164 offset:54272
	ds_read_b128 v[202:205], v164 offset:55296
	ds_read_b128 v[206:209], v164 offset:56320
	v_lshl_add_u64 v[226:227], v[136:137], 0, s[42:43]
	global_load_lds_dwordx4 v[226:227], off
	v_lshl_add_u64 v[226:227], v[226:227], 0, s[10:11]
	s_mov_b32 m0, s20
	s_nop 0
	global_load_lds_dwordx4 v[226:227], off
	s_barrier
; #define STA(b, h, half, kt) STAGE(((b) * 2 + (h)) * G_HT * 2, pA, ((size_t)(half) * G_HALF * lda + (size_t)(kt) * G_BK) * 2, lda)
; #define STB(b, h, half, kt) STAGE((4 + (b) * 2 + (h)) * G_HT * 2, pB, ((size_t)(half) * G_HALF * K + (size_t)(kt) * G_BK) * 2, K)
; #define LDA(dst, b, h) for (int m = 0; m < 4; ++m) for (int k = 0; k < 2; ++k) \
;     dst[m][k] = *reinterpret_cast<const bf16x8*>(aRd + (((b) * 2 + (h)) * G_HT * 2 + m * 2048 + k * 1024))
; #define LDB(dst, b, h) for (int n = 0; n < 2; ++n) for (int k = 0; k < 2; ++k) \
;     dst[n][k] = *reinterpret_cast<const bf16x8*>(bRd + (((b) * 2 + (h)) * G_HT * 2 + n * 2048 + k * 1024))
; #define MMA(ai, bj, At, Bx) do { __builtin_amdgcn_s_setprio(1); \
;     for (int m = 0; m < 4; ++m) for (int n = 0; n < 2; ++n) for (int k = 0; k < 2; ++k) \
;       acc[ai][bj][m][n] = __builtin_amdgcn_mfma_f32_16x16x32_bf16(Bx[n][k], At[m][k], acc[ai][bj][m][n], 0, 0, 0);     \
;     __builtin_amdgcn_s_setprio(0); } while (0)
; #define WAIT_V(n) asm volatile("s_waitcnt vmcnt(" #n ")" ::: "memory")
; #define WAIT_L(n) asm volatile("s_waitcnt lgkmcnt(" #n ")" ::: "memory")
; #define BAR __builtin_amdgcn_s_barrier()
; #define SCHED __builtin_amdgcn_sched_barrier(0)
; template <int EPI>
; __device__ __forceinline__ void gemm_tile(const bf16* __restrict__ A, int lda, const bf16* __restrict__ Bt, int K,
;                                           int brow, int bcol, const EpiArgs& ea, char* shmc, bool has_next, int nbrow, int nbcol, bool first_tile) {
;     ...
;     BAR; WAIT_L(0); MMA(1, 0, At, B0); BAR; SCHED;
;     STB(1, 1, 1, t + 3);
;     WAIT_V(6); BAR; MMA(1, 1, At, B1); BAR;
;   }
;   { LDB(B0, 0, 0); LDA(At, 0, 0); STA(1, 1, 1, nt - 1);
;     BAR; WAIT_L(0); MMA(0, 0, At, B0); BAR;
;     LDB(B1, 0, 1); BAR; WAIT_L(0); MMA(0, 1, At, B1); BAR;
	s_waitcnt lgkmcnt(0)
	v_mfma_f32_16x16x32_bf16 v[60:63], v[140:143], v[178:181], v[60:63]
	v_mfma_f32_16x16x32_bf16 v[56:59], v[170:173], v[178:181], v[56:59]
	v_mfma_f32_16x16x32_bf16 v[52:55], v[140:143], v[186:189], v[52:55]
	v_mfma_f32_16x16x32_bf16 v[48:51], v[170:173], v[186:189], v[48:51]
	v_mfma_f32_16x16x32_bf16 v[44:47], v[140:143], v[194:197], v[44:47]
	v_mfma_f32_16x16x32_bf16 v[40:43], v[170:173], v[194:197], v[40:43]
	v_mfma_f32_16x16x32_bf16 v[36:39], v[140:143], v[202:205], v[36:39]
	v_mfma_f32_16x16x32_bf16 v[32:35], v[170:173], v[202:205], v[32:35]
	v_mfma_f32_16x16x32_bf16 v[60:63], v[166:169], v[182:185], v[60:63]
	v_mfma_f32_16x16x32_bf16 v[56:59], v[174:177], v[182:185], v[56:59]
	v_mfma_f32_16x16x32_bf16 v[52:55], v[166:169], v[190:193], v[52:55]
	v_mfma_f32_16x16x32_bf16 v[48:51], v[174:177], v[190:193], v[48:51]
	v_mfma_f32_16x16x32_bf16 v[44:47], v[166:169], v[198:201], v[44:47]
	v_mfma_f32_16x16x32_bf16 v[40:43], v[174:177], v[198:201], v[40:43]
	v_mfma_f32_16x16x32_bf16 v[36:39], v[166:169], v[206:209], v[36:39]
	v_mfma_f32_16x16x32_bf16 v[32:35], v[174:177], v[206:209], v[32:35]
	s_barrier
	s_mov_b64 s[42:43], s[14:15]
	s_mov_b32 m0, s22
	v_lshl_add_u64 v[140:141], v[138:139], 0, s[42:43]
	global_load_lds_dwordx4 v[140:141], off
	v_lshl_add_u64 v[140:141], v[140:141], 0, s[10:11]
	s_mov_b32 m0, s23
	s_nop 0
	global_load_lds_dwordx4 v[140:141], off
	s_waitcnt vmcnt(6)
	s_barrier
	v_mfma_f32_16x16x32_bf16 v[28:31], v[210:213], v[178:181], v[28:31]
	v_mfma_f32_16x16x32_bf16 v[24:27], v[218:221], v[178:181], v[24:27]
	v_mfma_f32_16x16x32_bf16 v[20:23], v[210:213], v[186:189], v[20:23]
	v_mfma_f32_16x16x32_bf16 v[16:19], v[218:221], v[186:189], v[16:19]
	v_mfma_f32_16x16x32_bf16 v[12:15], v[210:213], v[194:197], v[12:15]
	v_mfma_f32_16x16x32_bf16 v[8:11], v[218:221], v[194:197], v[8:11]
	v_mfma_f32_16x16x32_bf16 v[4:7], v[210:213], v[202:205], v[4:7]
	v_mfma_f32_16x16x32_bf16 v[0:3], v[218:221], v[202:205], v[0:3]
	v_mfma_f32_16x16x32_bf16 v[28:31], v[214:217], v[182:185], v[28:31]
	v_mfma_f32_16x16x32_bf16 v[24:27], v[222:225], v[182:185], v[24:27]
	v_mfma_f32_16x16x32_bf16 v[20:23], v[214:217], v[190:193], v[20:23]
	v_mfma_f32_16x16x32_bf16 v[16:19], v[222:225], v[190:193], v[16:19]
	v_mfma_f32_16x16x32_bf16 v[12:15], v[214:217], v[198:201], v[12:15]
	v_mfma_f32_16x16x32_bf16 v[8:11], v[222:225], v[198:201], v[8:11]
	v_mfma_f32_16x16x32_bf16 v[4:7], v[214:217], v[206:209], v[4:7]
	v_mfma_f32_16x16x32_bf16 v[0:3], v[222:225], v[206:209], v[0:3]
	s_add_i32 s28, s28, 2
	s_add_u32 s14, s14, 0x100
	s_addc_u32 s15, s15, 0
	s_cmp_lt_u32 s28, 60
	s_barrier
	s_cbranch_scc1 .LBB0_654
	s_mov_b64 s[14:15], 0x101f80
	s_mov_b32 m0, s29
	ds_read_b128 v[138:141], v145
	ds_read_b128 v[166:169], v146
	ds_read_b128 v[170:173], v147
	ds_read_b128 v[174:177], v148
	ds_read_b128 v[178:181], v164
	ds_read_b128 v[182:185], v164 offset:1024
	ds_read_b128 v[186:189], v164 offset:2048
	ds_read_b128 v[190:193], v164 offset:3072
	ds_read_b128 v[194:197], v164 offset:4096
	ds_read_b128 v[198:201], v164 offset:5120
	ds_read_b128 v[202:205], v164 offset:6144
	ds_read_b128 v[206:209], v164 offset:7168
	s_nop 0
	v_lshl_add_u64 v[136:137], v[136:137], 0, s[14:15]
	global_load_lds_dwordx4 v[136:137], off
	v_lshl_add_u64 v[136:137], v[136:137], 0, s[10:11]
	s_mov_b32 m0, s21
	s_nop 0
	global_load_lds_dwordx4 v[136:137], off
	s_barrier
	s_waitcnt lgkmcnt(0)
	s_setprio 1
	s_waitcnt lgkmcnt(0)
	v_mfma_f32_16x16x32_bf16 v[124:127], v[138:141], v[178:181], v[124:127]
	v_mfma_f32_16x16x32_bf16 v[116:119], v[138:141], v[186:189], v[116:119]
	v_mfma_f32_16x16x32_bf16 v[112:115], v[170:173], v[186:189], v[112:115]
	v_mfma_f32_16x16x32_bf16 v[100:103], v[138:141], v[202:205], v[100:103]
	v_mfma_f32_16x16x32_bf16 v[96:99], v[170:173], v[202:205], v[96:99]
	v_mfma_f32_16x16x32_bf16 v[124:127], v[166:169], v[182:185], v[124:127]
	v_mfma_f32_16x16x32_bf16 v[120:123], v[170:173], v[178:181], v[120:123]
	v_mfma_f32_16x16x32_bf16 v[116:119], v[166:169], v[190:193], v[116:119]
	v_mfma_f32_16x16x32_bf16 v[112:115], v[174:177], v[190:193], v[112:115]
	v_mfma_f32_16x16x32_bf16 v[108:111], v[138:141], v[194:197], v[108:111]
	v_mfma_f32_16x16x32_bf16 v[104:107], v[170:173], v[194:197], v[104:107]
	v_mfma_f32_16x16x32_bf16 v[100:103], v[166:169], v[206:209], v[100:103]
	v_mfma_f32_16x16x32_bf16 v[96:99], v[174:177], v[206:209], v[96:99]
	v_mfma_f32_16x16x32_bf16 v[210:213], v[174:177], v[182:185], v[120:123]
	v_mfma_f32_16x16x32_bf16 v[214:217], v[166:169], v[198:201], v[108:111]
	v_mfma_f32_16x16x32_bf16 v[218:221], v[174:177], v[198:201], v[104:107]
	s_setprio 0
	s_barrier
	s_nop 0
	ds_read_b128 v[104:107], v149
	ds_read_b128 v[108:111], v150
	ds_read_b128 v[120:123], v151
	ds_read_b128 v[222:225], v152
	s_barrier
	s_waitcnt lgkmcnt(0)
	s_setprio 1
	s_waitcnt lgkmcnt(0)
	v_mfma_f32_16x16x32_bf16 v[84:87], v[104:107], v[186:189], v[84:87]
	v_mfma_f32_16x16x32_bf16 v[80:83], v[120:123], v[186:189], v[80:83]
	v_mfma_f32_16x16x32_bf16 v[68:71], v[104:107], v[202:205], v[68:71]
	v_mfma_f32_16x16x32_bf16 v[92:95], v[104:107], v[178:181], v[92:95]
	v_mfma_f32_16x16x32_bf16 v[88:91], v[120:123], v[178:181], v[88:91]
	v_mfma_f32_16x16x32_bf16 v[84:87], v[108:111], v[190:193], v[84:87]
	v_mfma_f32_16x16x32_bf16 v[80:83], v[222:225], v[190:193], v[80:83]
	v_mfma_f32_16x16x32_bf16 v[76:79], v[104:107], v[194:197], v[76:79]
	v_mfma_f32_16x16x32_bf16 v[72:75], v[120:123], v[194:197], v[72:75]
	v_mfma_f32_16x16x32_bf16 v[68:71], v[108:111], v[206:209], v[68:71]
	v_mfma_f32_16x16x32_bf16 v[64:67], v[120:123], v[202:205], v[64:67]
	v_mfma_f32_16x16x32_bf16 v[226:229], v[108:111], v[182:185], v[92:95]
	v_mfma_f32_16x16x32_bf16 v[178:181], v[222:225], v[182:185], v[88:91]
	v_mfma_f32_16x16x32_bf16 v[182:185], v[108:111], v[198:201], v[76:79]
	v_mfma_f32_16x16x32_bf16 v[186:189], v[222:225], v[198:201], v[72:75]
	v_mfma_f32_16x16x32_bf16 v[190:193], v[222:225], v[206:209], v[64:67]
	s_setprio 0
	s_barrier
	s_nop 0
	ds_read_b128 v[64:67], v164 offset:16384
	ds_read_b128 v[72:75], v164 offset:17408
	ds_read_b128 v[76:79], v164 offset:18432
	ds_read_b128 v[88:91], v164 offset:19456
	ds_read_b128 v[92:95], v164 offset:20480
	ds_read_b128 v[194:197], v164 offset:21504
	ds_read_b128 v[198:201], v164 offset:22528
	ds_read_b128 v[202:205], v164 offset:23552
	s_waitcnt vmcnt(4)
	s_barrier
	s_waitcnt lgkmcnt(0)
	s_setprio 1
	s_waitcnt lgkmcnt(0)
	v_mfma_f32_16x16x32_bf16 v[60:63], v[138:141], v[64:67], v[60:63]
	v_mfma_f32_16x16x32_bf16 v[52:55], v[138:141], v[76:79], v[52:55]
	v_mfma_f32_16x16x32_bf16 v[48:51], v[170:173], v[76:79], v[48:51]
	v_mfma_f32_16x16x32_bf16 v[36:39], v[138:141], v[198:201], v[36:39]
	v_mfma_f32_16x16x32_bf16 v[32:35], v[170:173], v[198:201], v[32:35]
	v_mfma_f32_16x16x32_bf16 v[60:63], v[166:169], v[72:75], v[60:63]
	v_mfma_f32_16x16x32_bf16 v[56:59], v[170:173], v[64:67], v[56:59]
	v_mfma_f32_16x16x32_bf16 v[52:55], v[166:169], v[88:91], v[52:55]
	v_mfma_f32_16x16x32_bf16 v[48:51], v[174:177], v[88:91], v[48:51]
	v_mfma_f32_16x16x32_bf16 v[44:47], v[138:141], v[92:95], v[44:47]
	v_mfma_f32_16x16x32_bf16 v[40:43], v[170:173], v[92:95], v[40:43]
	v_mfma_f32_16x16x32_bf16 v[36:39], v[166:169], v[202:205], v[36:39]
	v_mfma_f32_16x16x32_bf16 v[32:35], v[174:177], v[202:205], v[32:35]
	v_mfma_f32_16x16x32_bf16 v[206:209], v[174:177], v[72:75], v[56:59]
	v_mfma_f32_16x16x32_bf16 v[230:233], v[166:169], v[194:197], v[44:47]
	v_mfma_f32_16x16x32_bf16 v[234:237], v[174:177], v[194:197], v[40:43]
	s_setprio 0
	s_setprio 1
	v_mfma_f32_16x16x32_bf16 v[20:23], v[104:107], v[76:79], v[20:23]
	v_mfma_f32_16x16x32_bf16 v[16:19], v[120:123], v[76:79], v[16:19]
	v_mfma_f32_16x16x32_bf16 v[4:7], v[104:107], v[198:201], v[4:7]
	v_mfma_f32_16x16x32_bf16 v[28:31], v[104:107], v[64:67], v[28:31]
	v_mfma_f32_16x16x32_bf16 v[24:27], v[120:123], v[64:67], v[24:27]
	v_mfma_f32_16x16x32_bf16 v[20:23], v[108:111], v[88:91], v[20:23]
	v_mfma_f32_16x16x32_bf16 v[16:19], v[222:225], v[88:91], v[16:19]
	v_mfma_f32_16x16x32_bf16 v[12:15], v[104:107], v[92:95], v[12:15]
	v_mfma_f32_16x16x32_bf16 v[8:11], v[120:123], v[92:95], v[8:11]
	v_mfma_f32_16x16x32_bf16 v[4:7], v[108:111], v[202:205], v[4:7]
	v_mfma_f32_16x16x32_bf16 v[0:3], v[120:123], v[198:201], v[0:3]
	v_mfma_f32_16x16x32_bf16 v[136:139], v[108:111], v[72:75], v[28:31]
	v_mfma_f32_16x16x32_bf16 v[140:143], v[222:225], v[72:75], v[24:27]
	v_mfma_f32_16x16x32_bf16 v[166:169], v[108:111], v[194:197], v[12:15]
	v_mfma_f32_16x16x32_bf16 v[170:173], v[222:225], v[194:197], v[8:11]
	v_mfma_f32_16x16x32_bf16 v[174:177], v[222:225], v[202:205], v[0:3]
	s_setprio 0
	s_barrier
	s_nop 0
	ds_read_b128 v[0:3], v153
	ds_read_b128 v[8:11], v154
	ds_read_b128 v[12:15], v155
	ds_read_b128 v[194:197], v156
	ds_read_b128 v[24:27], v164 offset:32768
	ds_read_b128 v[28:31], v164 offset:33792
	ds_read_b128 v[40:43], v164 offset:34816
	ds_read_b128 v[44:47], v164 offset:35840
	ds_read_b128 v[56:59], v164 offset:36864
	ds_read_b128 v[64:67], v164 offset:37888
	ds_read_b128 v[198:201], v164 offset:38912
	ds_read_b128 v[202:205], v164 offset:39936
	s_waitcnt vmcnt(2)
	s_barrier
	s_waitcnt lgkmcnt(0)
	s_setprio 1
	s_waitcnt lgkmcnt(0)
	v_mfma_f32_16x16x32_bf16 v[72:75], v[0:3], v[24:27], v[124:127]
	v_mfma_f32_16x16x32_bf16 v[120:123], v[8:11], v[28:31], v[72:75]
	v_mfma_f32_16x16x32_bf16 v[72:75], v[12:15], v[24:27], v[210:213]
	v_mfma_f32_16x16x32_bf16 v[124:127], v[194:197], v[28:31], v[72:75]
	v_mfma_f32_16x16x32_bf16 v[72:75], v[0:3], v[40:43], v[116:119]
	v_mfma_f32_16x16x32_bf16 v[104:107], v[8:11], v[44:47], v[72:75]
	v_mfma_f32_16x16x32_bf16 v[72:75], v[12:15], v[40:43], v[112:115]
	v_mfma_f32_16x16x32_bf16 v[108:111], v[194:197], v[44:47], v[72:75]
	v_mfma_f32_16x16x32_bf16 v[72:75], v[0:3], v[56:59], v[214:217]
	v_mfma_f32_16x16x32_bf16 v[88:91], v[8:11], v[64:67], v[72:75]
	v_mfma_f32_16x16x32_bf16 v[72:75], v[12:15], v[56:59], v[218:221]
	v_mfma_f32_16x16x32_bf16 v[92:95], v[194:197], v[64:67], v[72:75]
	v_mfma_f32_16x16x32_bf16 v[72:75], v[0:3], v[198:201], v[100:103]
	v_mfma_f32_16x16x32_bf16 v[76:79], v[12:15], v[198:201], v[96:99]
	v_mfma_f32_16x16x32_bf16 v[72:75], v[8:11], v[202:205], v[72:75]
	v_mfma_f32_16x16x32_bf16 v[76:79], v[194:197], v[202:205], v[76:79]
	s_setprio 0
	s_barrier
	ds_read_b128 v[210:213], v158
	ds_read_b128 v[214:217], v159
	ds_read_b128 v[218:221], v160
	ds_read_b128 v[222:225], v161
	s_waitcnt vmcnt(0)
	s_barrier
	s_waitcnt lgkmcnt(0)
	s_setprio 1
	s_waitcnt lgkmcnt(0)
	v_mfma_f32_16x16x32_bf16 v[96:99], v[210:213], v[24:27], v[226:229]
	v_mfma_f32_16x16x32_bf16 v[24:27], v[218:221], v[24:27], v[178:181]
	v_mfma_f32_16x16x32_bf16 v[116:119], v[222:225], v[28:31], v[24:27]
	v_mfma_f32_16x16x32_bf16 v[24:27], v[210:213], v[40:43], v[84:87]
	v_mfma_f32_16x16x32_bf16 v[112:115], v[214:217], v[28:31], v[96:99]
	v_mfma_f32_16x16x32_bf16 v[96:99], v[214:217], v[44:47], v[24:27]
	v_mfma_f32_16x16x32_bf16 v[24:27], v[218:221], v[40:43], v[80:83]
	v_mfma_f32_16x16x32_bf16 v[100:103], v[222:225], v[44:47], v[24:27]
	v_mfma_f32_16x16x32_bf16 v[24:27], v[210:213], v[56:59], v[182:185]
	v_mfma_f32_16x16x32_bf16 v[80:83], v[214:217], v[64:67], v[24:27]
	v_mfma_f32_16x16x32_bf16 v[24:27], v[218:221], v[56:59], v[186:189]
	v_mfma_f32_16x16x32_bf16 v[84:87], v[222:225], v[64:67], v[24:27]
	v_mfma_f32_16x16x32_bf16 v[24:27], v[210:213], v[198:201], v[68:71]
	v_mfma_f32_16x16x32_bf16 v[64:67], v[214:217], v[202:205], v[24:27]
	v_mfma_f32_16x16x32_bf16 v[24:27], v[218:221], v[198:201], v[190:193]
	v_mfma_f32_16x16x32_bf16 v[68:71], v[222:225], v[202:205], v[24:27]
	s_setprio 0
	s_barrier
	ds_read_b128 v[178:181], v164 offset:49152
	ds_read_b128 v[182:185], v164 offset:50176
	ds_read_b128 v[186:189], v164 offset:51200
	ds_read_b128 v[190:193], v164 offset:52224
	ds_read_b128 v[198:201], v164 offset:53248
	ds_read_b128 v[202:205], v164 offset:54272
	ds_read_b128 v[226:229], v164 offset:55296
	ds_read_b128 v[238:241], v164 offset:56320
	s_barrier
	s_waitcnt lgkmcnt(0)
	s_setprio 1
	s_waitcnt lgkmcnt(0)
	v_mfma_f32_16x16x32_bf16 v[24:27], v[0:3], v[178:181], v[60:63]
	v_mfma_f32_16x16x32_bf16 v[56:59], v[8:11], v[182:185], v[24:27]
	v_mfma_f32_16x16x32_bf16 v[24:27], v[12:15], v[178:181], v[206:209]
	v_mfma_f32_16x16x32_bf16 v[60:63], v[194:197], v[182:185], v[24:27]
	v_mfma_f32_16x16x32_bf16 v[24:27], v[0:3], v[186:189], v[52:55]
	v_mfma_f32_16x16x32_bf16 v[40:43], v[8:11], v[190:193], v[24:27]
	v_mfma_f32_16x16x32_bf16 v[24:27], v[12:15], v[186:189], v[48:51]
	v_mfma_f32_16x16x32_bf16 v[44:47], v[194:197], v[190:193], v[24:27]
	v_mfma_f32_16x16x32_bf16 v[24:27], v[0:3], v[198:201], v[230:233]
	v_mfma_f32_16x16x32_bf16 v[0:3], v[0:3], v[226:229], v[36:39]
	v_mfma_f32_16x16x32_bf16 v[24:27], v[8:11], v[202:205], v[24:27]
	v_mfma_f32_16x16x32_bf16 v[28:31], v[12:15], v[198:201], v[234:237]
	v_mfma_f32_16x16x32_bf16 v[8:11], v[8:11], v[238:241], v[0:3]
	v_mfma_f32_16x16x32_bf16 v[0:3], v[12:15], v[226:229], v[32:35]
	v_mfma_f32_16x16x32_bf16 v[28:31], v[194:197], v[202:205], v[28:31]
	v_mfma_f32_16x16x32_bf16 v[12:15], v[194:197], v[238:241], v[0:3]
	s_setprio 0
	s_setprio 1
	v_mfma_f32_16x16x32_bf16 v[0:3], v[210:213], v[178:181], v[136:139]
	v_mfma_f32_16x16x32_bf16 v[48:51], v[214:217], v[182:185], v[0:3]
	v_mfma_f32_16x16x32_bf16 v[0:3], v[218:221], v[178:181], v[140:143]
	v_mfma_f32_16x16x32_bf16 v[52:55], v[222:225], v[182:185], v[0:3]
	v_mfma_f32_16x16x32_bf16 v[0:3], v[210:213], v[186:189], v[20:23]
	v_mfma_f32_16x16x32_bf16 v[32:35], v[214:217], v[190:193], v[0:3]
	v_mfma_f32_16x16x32_bf16 v[0:3], v[218:221], v[186:189], v[16:19]
	v_mfma_f32_16x16x32_bf16 v[36:39], v[222:225], v[190:193], v[0:3]
	v_mfma_f32_16x16x32_bf16 v[0:3], v[210:213], v[198:201], v[166:169]
	v_mfma_f32_16x16x32_bf16 v[16:19], v[214:217], v[202:205], v[0:3]
	v_mfma_f32_16x16x32_bf16 v[0:3], v[218:221], v[198:201], v[170:173]
	v_mfma_f32_16x16x32_bf16 v[20:23], v[222:225], v[202:205], v[0:3]
	v_mfma_f32_16x16x32_bf16 v[0:3], v[210:213], v[226:229], v[4:7]
	v_mfma_f32_16x16x32_bf16 v[4:7], v[218:221], v[226:229], v[174:177]
	v_mfma_f32_16x16x32_bf16 v[0:3], v[214:217], v[238:241], v[0:3]
	v_mfma_f32_16x16x32_bf16 v[4:7], v[222:225], v[238:241], v[4:7]
	s_setprio 0
	s_barrier
	s_and_saveexec_b64 s[14:15], s[4:5]
	s_cbranch_execz .LBB0_657
	s_barrier

.LBB0_727:
	ds_read_b128 v[136:139], v141
	ds_read_b128 v[162:165], v142
	ds_read_b128 v[166:169], v143
	ds_read_b128 v[170:173], v144
	s_add_u32 s52, s20, 0xffffff00
	s_addc_u32 s53, s21, -1
	s_mov_b32 m0, s50
	ds_read_b128 v[174:177], v160
	ds_read_b128 v[178:181], v160 offset:1024
	ds_read_b128 v[182:185], v160 offset:2048
	ds_read_b128 v[186:189], v160 offset:3072
	ds_read_b128 v[190:193], v160 offset:4096
	ds_read_b128 v[194:197], v160 offset:5120
	ds_read_b128 v[198:201], v160 offset:6144
	ds_read_b128 v[202:205], v160 offset:7168
	v_lshl_add_u64 v[206:207], v[132:133], 0, s[52:53]
	global_load_lds_dwordx4 v[206:207], off
	v_lshl_add_u64 v[206:207], v[206:207], 0, s[10:11]
	s_mov_b32 m0, s34
	s_nop 0
	global_load_lds_dwordx4 v[206:207], off
	s_waitcnt lgkmcnt(8)
	s_barrier
	s_waitcnt lgkmcnt(0)
	v_mfma_f32_16x16x32_bf16 v[124:127], v[136:139], v[174:177], v[124:127]
	v_mfma_f32_16x16x32_bf16 v[120:123], v[166:169], v[174:177], v[120:123]
	v_mfma_f32_16x16x32_bf16 v[116:119], v[136:139], v[182:185], v[116:119]
	v_mfma_f32_16x16x32_bf16 v[112:115], v[166:169], v[182:185], v[112:115]
	v_mfma_f32_16x16x32_bf16 v[108:111], v[136:139], v[190:193], v[108:111]
	v_mfma_f32_16x16x32_bf16 v[104:107], v[166:169], v[190:193], v[104:107]
	v_mfma_f32_16x16x32_bf16 v[100:103], v[136:139], v[198:201], v[100:103]
	v_mfma_f32_16x16x32_bf16 v[96:99], v[166:169], v[198:201], v[96:99]
	v_mfma_f32_16x16x32_bf16 v[124:127], v[162:165], v[178:181], v[124:127]
	v_mfma_f32_16x16x32_bf16 v[120:123], v[170:173], v[178:181], v[120:123]
	v_mfma_f32_16x16x32_bf16 v[116:119], v[162:165], v[186:189], v[116:119]
	v_mfma_f32_16x16x32_bf16 v[112:115], v[170:173], v[186:189], v[112:115]
	v_mfma_f32_16x16x32_bf16 v[108:111], v[162:165], v[194:197], v[108:111]
	v_mfma_f32_16x16x32_bf16 v[104:107], v[170:173], v[194:197], v[104:107]
	v_mfma_f32_16x16x32_bf16 v[100:103], v[162:165], v[202:205], v[100:103]
	v_mfma_f32_16x16x32_bf16 v[96:99], v[170:173], v[202:205], v[96:99]
	s_barrier
	s_add_u32 s52, s20, 0xffefff80
	s_addc_u32 s53, s21, -1
	s_mov_b64 s[54:55], s[52:53]
	s_mov_b32 m0, s41
	ds_read_b128 v[206:209], v145
	ds_read_b128 v[210:213], v146
	ds_read_b128 v[214:217], v147
	ds_read_b128 v[218:221], v148
	v_lshl_add_u64 v[222:223], v[134:135], 0, s[54:55]
	global_load_lds_dwordx4 v[222:223], off
	v_lshl_add_u64 v[222:223], v[222:223], 0, s[10:11]
	s_mov_b32 m0, s42
	s_nop 0
	global_load_lds_dwordx4 v[222:223], off
	s_barrier
	s_waitcnt lgkmcnt(0)
	v_mfma_f32_16x16x32_bf16 v[92:95], v[206:209], v[174:177], v[92:95]
	v_mfma_f32_16x16x32_bf16 v[88:91], v[214:217], v[174:177], v[88:91]
	v_mfma_f32_16x16x32_bf16 v[84:87], v[206:209], v[182:185], v[84:87]
	v_mfma_f32_16x16x32_bf16 v[80:83], v[214:217], v[182:185], v[80:83]
	v_mfma_f32_16x16x32_bf16 v[76:79], v[206:209], v[190:193], v[76:79]
	v_mfma_f32_16x16x32_bf16 v[72:75], v[214:217], v[190:193], v[72:75]
	v_mfma_f32_16x16x32_bf16 v[68:71], v[206:209], v[198:201], v[68:71]
	v_mfma_f32_16x16x32_bf16 v[64:67], v[214:217], v[198:201], v[64:67]
	v_mfma_f32_16x16x32_bf16 v[92:95], v[210:213], v[178:181], v[92:95]
	v_mfma_f32_16x16x32_bf16 v[88:91], v[218:221], v[178:181], v[88:91]
	v_mfma_f32_16x16x32_bf16 v[84:87], v[210:213], v[186:189], v[84:87]
	v_mfma_f32_16x16x32_bf16 v[80:83], v[218:221], v[186:189], v[80:83]
	v_mfma_f32_16x16x32_bf16 v[76:79], v[210:213], v[194:197], v[76:79]
	v_mfma_f32_16x16x32_bf16 v[72:75], v[218:221], v[194:197], v[72:75]
	v_mfma_f32_16x16x32_bf16 v[68:71], v[210:213], v[202:205], v[68:71]
	v_mfma_f32_16x16x32_bf16 v[64:67], v[218:221], v[202:205], v[64:67]
	s_mov_b32 m0, s1
	s_barrier
	ds_read_b128 v[174:177], v160 offset:16384
	ds_read_b128 v[178:181], v160 offset:17408
	ds_read_b128 v[182:185], v160 offset:18432
	ds_read_b128 v[186:189], v160 offset:19456
	ds_read_b128 v[190:193], v160 offset:20480
	ds_read_b128 v[194:197], v160 offset:21504
	ds_read_b128 v[198:201], v160 offset:22528
	ds_read_b128 v[202:205], v160 offset:23552
	v_lshl_add_u64 v[222:223], v[132:133], 0, s[52:53]
	global_load_lds_dwordx4 v[222:223], off
	v_lshl_add_u64 v[222:223], v[222:223], 0, s[10:11]
	s_add_i32 m0, s1, 0x2000
	s_nop 0
	global_load_lds_dwordx4 v[222:223], off
	s_barrier
	s_waitcnt lgkmcnt(0)
	v_mfma_f32_16x16x32_bf16 v[60:63], v[136:139], v[174:177], v[60:63]
	v_mfma_f32_16x16x32_bf16 v[56:59], v[166:169], v[174:177], v[56:59]
	v_mfma_f32_16x16x32_bf16 v[52:55], v[136:139], v[182:185], v[52:55]
	v_mfma_f32_16x16x32_bf16 v[48:51], v[166:169], v[182:185], v[48:51]
	v_mfma_f32_16x16x32_bf16 v[44:47], v[136:139], v[190:193], v[44:47]
	v_mfma_f32_16x16x32_bf16 v[40:43], v[166:169], v[190:193], v[40:43]
	v_mfma_f32_16x16x32_bf16 v[36:39], v[136:139], v[198:201], v[36:39]
	v_mfma_f32_16x16x32_bf16 v[32:35], v[166:169], v[198:201], v[32:35]
	v_mfma_f32_16x16x32_bf16 v[60:63], v[162:165], v[178:181], v[60:63]
	v_mfma_f32_16x16x32_bf16 v[56:59], v[170:173], v[178:181], v[56:59]
	v_mfma_f32_16x16x32_bf16 v[52:55], v[162:165], v[186:189], v[52:55]
	v_mfma_f32_16x16x32_bf16 v[48:51], v[170:173], v[186:189], v[48:51]
	v_mfma_f32_16x16x32_bf16 v[44:47], v[162:165], v[194:197], v[44:47]
	v_mfma_f32_16x16x32_bf16 v[40:43], v[170:173], v[194:197], v[40:43]
	v_mfma_f32_16x16x32_bf16 v[36:39], v[162:165], v[202:205], v[36:39]
	v_mfma_f32_16x16x32_bf16 v[32:35], v[170:173], v[202:205], v[32:35]
	s_barrier
	s_add_u32 s52, s20, 0xffffff80
	s_addc_u32 s53, s21, -1
	s_mov_b64 s[54:55], s[52:53]
	s_mov_b32 m0, s43
	v_lshl_add_u64 v[136:137], v[134:135], 0, s[54:55]
	global_load_lds_dwordx4 v[136:137], off
	v_lshl_add_u64 v[136:137], v[136:137], 0, s[10:11]
	s_mov_b32 m0, s48
	s_nop 0
	global_load_lds_dwordx4 v[136:137], off
	s_waitcnt vmcnt(6)
	s_barrier
	v_mfma_f32_16x16x32_bf16 v[28:31], v[206:209], v[174:177], v[28:31]
	v_mfma_f32_16x16x32_bf16 v[24:27], v[214:217], v[174:177], v[24:27]
	v_mfma_f32_16x16x32_bf16 v[20:23], v[206:209], v[182:185], v[20:23]
	v_mfma_f32_16x16x32_bf16 v[16:19], v[214:217], v[182:185], v[16:19]
	v_mfma_f32_16x16x32_bf16 v[12:15], v[206:209], v[190:193], v[12:15]
	v_mfma_f32_16x16x32_bf16 v[8:11], v[214:217], v[190:193], v[8:11]
	v_mfma_f32_16x16x32_bf16 v[4:7], v[206:209], v[198:201], v[4:7]
	v_mfma_f32_16x16x32_bf16 v[0:3], v[214:217], v[198:201], v[0:3]
	v_mfma_f32_16x16x32_bf16 v[28:31], v[210:213], v[178:181], v[28:31]
	v_mfma_f32_16x16x32_bf16 v[24:27], v[218:221], v[178:181], v[24:27]
	v_mfma_f32_16x16x32_bf16 v[20:23], v[210:213], v[186:189], v[20:23]
	v_mfma_f32_16x16x32_bf16 v[16:19], v[218:221], v[186:189], v[16:19]
	v_mfma_f32_16x16x32_bf16 v[12:15], v[210:213], v[194:197], v[12:15]
	v_mfma_f32_16x16x32_bf16 v[8:11], v[218:221], v[194:197], v[8:11]
	v_mfma_f32_16x16x32_bf16 v[4:7], v[210:213], v[202:205], v[4:7]
	v_mfma_f32_16x16x32_bf16 v[0:3], v[218:221], v[202:205], v[0:3]
	s_barrier
	ds_read_b128 v[136:139], v149
	ds_read_b128 v[162:165], v150
	ds_read_b128 v[166:169], v151
	ds_read_b128 v[170:173], v152
	ds_read_b128 v[174:177], v160 offset:32768
	ds_read_b128 v[178:181], v160 offset:33792
	ds_read_b128 v[182:185], v160 offset:34816
	ds_read_b128 v[186:189], v160 offset:35840
	ds_read_b128 v[190:193], v160 offset:36864
	ds_read_b128 v[194:197], v160 offset:37888
	ds_read_b128 v[198:201], v160 offset:38912
	ds_read_b128 v[202:205], v160 offset:39936
	s_add_i32 m0, s1, 0x4000
	v_lshl_add_u64 v[206:207], v[132:133], 0, s[52:53]
	global_load_lds_dwordx4 v[206:207], off
	v_lshl_add_u64 v[206:207], v[206:207], 0, s[10:11]
	s_add_i32 m0, s1, 0x6000
	s_nop 0
	global_load_lds_dwordx4 v[206:207], off
	s_waitcnt lgkmcnt(8)
	s_barrier
	s_waitcnt lgkmcnt(0)
	v_mfma_f32_16x16x32_bf16 v[124:127], v[136:139], v[174:177], v[124:127]
	v_mfma_f32_16x16x32_bf16 v[120:123], v[166:169], v[174:177], v[120:123]
	v_mfma_f32_16x16x32_bf16 v[116:119], v[136:139], v[182:185], v[116:119]
	v_mfma_f32_16x16x32_bf16 v[112:115], v[166:169], v[182:185], v[112:115]
	v_mfma_f32_16x16x32_bf16 v[108:111], v[136:139], v[190:193], v[108:111]
	v_mfma_f32_16x16x32_bf16 v[104:107], v[166:169], v[190:193], v[104:107]
	v_mfma_f32_16x16x32_bf16 v[100:103], v[136:139], v[198:201], v[100:103]
	v_mfma_f32_16x16x32_bf16 v[96:99], v[166:169], v[198:201], v[96:99]
	v_mfma_f32_16x16x32_bf16 v[124:127], v[162:165], v[178:181], v[124:127]
	v_mfma_f32_16x16x32_bf16 v[120:123], v[170:173], v[178:181], v[120:123]
	v_mfma_f32_16x16x32_bf16 v[116:119], v[162:165], v[186:189], v[116:119]
	v_mfma_f32_16x16x32_bf16 v[112:115], v[170:173], v[186:189], v[112:115]
	v_mfma_f32_16x16x32_bf16 v[108:111], v[162:165], v[194:197], v[108:111]
	v_mfma_f32_16x16x32_bf16 v[104:107], v[170:173], v[194:197], v[104:107]
	v_mfma_f32_16x16x32_bf16 v[100:103], v[162:165], v[202:205], v[100:103]
	v_mfma_f32_16x16x32_bf16 v[96:99], v[170:173], v[202:205], v[96:99]
	s_barrier
	s_add_u32 s52, s20, 0xfff00000
	s_addc_u32 s53, s21, -1
	s_mov_b64 s[54:55], s[52:53]
	s_mov_b32 m0, s7
	ds_read_b128 v[206:209], v153
	ds_read_b128 v[210:213], v154
	ds_read_b128 v[214:217], v155
	ds_read_b128 v[218:221], v156
	v_lshl_add_u64 v[222:223], v[134:135], 0, s[54:55]
	global_load_lds_dwordx4 v[222:223], off
	v_lshl_add_u64 v[222:223], v[222:223], 0, s[10:11]
	s_mov_b32 m0, s29
	s_nop 0
	global_load_lds_dwordx4 v[222:223], off
	s_barrier
	s_waitcnt lgkmcnt(0)
	v_mfma_f32_16x16x32_bf16 v[92:95], v[206:209], v[174:177], v[92:95]
	v_mfma_f32_16x16x32_bf16 v[88:91], v[214:217], v[174:177], v[88:91]
	v_mfma_f32_16x16x32_bf16 v[84:87], v[206:209], v[182:185], v[84:87]
	v_mfma_f32_16x16x32_bf16 v[80:83], v[214:217], v[182:185], v[80:83]
	v_mfma_f32_16x16x32_bf16 v[76:79], v[206:209], v[190:193], v[76:79]
	v_mfma_f32_16x16x32_bf16 v[72:75], v[214:217], v[190:193], v[72:75]
	v_mfma_f32_16x16x32_bf16 v[68:71], v[206:209], v[198:201], v[68:71]
	v_mfma_f32_16x16x32_bf16 v[64:67], v[214:217], v[198:201], v[64:67]
	v_mfma_f32_16x16x32_bf16 v[92:95], v[210:213], v[178:181], v[92:95]
	v_mfma_f32_16x16x32_bf16 v[88:91], v[218:221], v[178:181], v[88:91]
	v_mfma_f32_16x16x32_bf16 v[84:87], v[210:213], v[186:189], v[84:87]
	v_mfma_f32_16x16x32_bf16 v[80:83], v[218:221], v[186:189], v[80:83]
	v_mfma_f32_16x16x32_bf16 v[76:79], v[210:213], v[194:197], v[76:79]
	v_mfma_f32_16x16x32_bf16 v[72:75], v[218:221], v[194:197], v[72:75]
	v_mfma_f32_16x16x32_bf16 v[68:71], v[210:213], v[202:205], v[68:71]
	v_mfma_f32_16x16x32_bf16 v[64:67], v[218:221], v[202:205], v[64:67]
	s_mov_b32 m0, s30
	s_barrier
	ds_read_b128 v[174:177], v160 offset:49152
	ds_read_b128 v[178:181], v160 offset:50176
	ds_read_b128 v[182:185], v160 offset:51200
	ds_read_b128 v[186:189], v160 offset:52224
	ds_read_b128 v[190:193], v160 offset:53248
	ds_read_b128 v[194:197], v160 offset:54272
	ds_read_b128 v[198:201], v160 offset:55296
	ds_read_b128 v[202:205], v160 offset:56320
	v_lshl_add_u64 v[222:223], v[132:133], 0, s[52:53]
	global_load_lds_dwordx4 v[222:223], off
	v_lshl_add_u64 v[222:223], v[222:223], 0, s[10:11]
	s_mov_b32 m0, s31
	s_nop 0
	global_load_lds_dwordx4 v[222:223], off
	s_barrier
	s_waitcnt lgkmcnt(0)
	v_mfma_f32_16x16x32_bf16 v[60:63], v[136:139], v[174:177], v[60:63]
	v_mfma_f32_16x16x32_bf16 v[56:59], v[166:169], v[174:177], v[56:59]
	v_mfma_f32_16x16x32_bf16 v[52:55], v[136:139], v[182:185], v[52:55]
	v_mfma_f32_16x16x32_bf16 v[48:51], v[166:169], v[182:185], v[48:51]
	v_mfma_f32_16x16x32_bf16 v[44:47], v[136:139], v[190:193], v[44:47]
	v_mfma_f32_16x16x32_bf16 v[40:43], v[166:169], v[190:193], v[40:43]
	v_mfma_f32_16x16x32_bf16 v[36:39], v[136:139], v[198:201], v[36:39]
	v_mfma_f32_16x16x32_bf16 v[32:35], v[166:169], v[198:201], v[32:35]
	v_mfma_f32_16x16x32_bf16 v[60:63], v[162:165], v[178:181], v[60:63]
	v_mfma_f32_16x16x32_bf16 v[56:59], v[170:173], v[178:181], v[56:59]
	v_mfma_f32_16x16x32_bf16 v[52:55], v[162:165], v[186:189], v[52:55]
	v_mfma_f32_16x16x32_bf16 v[48:51], v[170:173], v[186:189], v[48:51]
	v_mfma_f32_16x16x32_bf16 v[44:47], v[162:165], v[194:197], v[44:47]
	v_mfma_f32_16x16x32_bf16 v[40:43], v[170:173], v[194:197], v[40:43]
	v_mfma_f32_16x16x32_bf16 v[36:39], v[162:165], v[202:205], v[36:39]
	v_mfma_f32_16x16x32_bf16 v[32:35], v[170:173], v[202:205], v[32:35]
	s_barrier
	s_mov_b64 s[52:53], s[20:21]
	s_mov_b32 m0, s35
	v_lshl_add_u64 v[136:137], v[134:135], 0, s[52:53]
	global_load_lds_dwordx4 v[136:137], off
	v_lshl_add_u64 v[136:137], v[136:137], 0, s[10:11]
	s_mov_b32 m0, s40
	s_nop 0
	global_load_lds_dwordx4 v[136:137], off
	s_waitcnt vmcnt(6)
	s_barrier
	v_mfma_f32_16x16x32_bf16 v[28:31], v[206:209], v[174:177], v[28:31]
	v_mfma_f32_16x16x32_bf16 v[24:27], v[214:217], v[174:177], v[24:27]
	v_mfma_f32_16x16x32_bf16 v[20:23], v[206:209], v[182:185], v[20:23]
	v_mfma_f32_16x16x32_bf16 v[16:19], v[214:217], v[182:185], v[16:19]
	v_mfma_f32_16x16x32_bf16 v[12:15], v[206:209], v[190:193], v[12:15]
	v_mfma_f32_16x16x32_bf16 v[8:11], v[214:217], v[190:193], v[8:11]
	v_mfma_f32_16x16x32_bf16 v[4:7], v[206:209], v[198:201], v[4:7]
	v_mfma_f32_16x16x32_bf16 v[0:3], v[214:217], v[198:201], v[0:3]
	v_mfma_f32_16x16x32_bf16 v[28:31], v[210:213], v[178:181], v[28:31]
	v_mfma_f32_16x16x32_bf16 v[24:27], v[218:221], v[178:181], v[24:27]
	v_mfma_f32_16x16x32_bf16 v[20:23], v[210:213], v[186:189], v[20:23]
	v_mfma_f32_16x16x32_bf16 v[16:19], v[218:221], v[186:189], v[16:19]
	v_mfma_f32_16x16x32_bf16 v[12:15], v[210:213], v[194:197], v[12:15]
	v_mfma_f32_16x16x32_bf16 v[8:11], v[218:221], v[194:197], v[8:11]
	v_mfma_f32_16x16x32_bf16 v[4:7], v[210:213], v[202:205], v[4:7]
	v_mfma_f32_16x16x32_bf16 v[0:3], v[218:221], v[202:205], v[0:3]
	s_add_i32 s49, s49, 2
	s_add_u32 s20, s20, 0x100
	s_addc_u32 s21, s21, 0
	s_cmp_lt_u32 s49, 60
	s_barrier
	s_cbranch_scc1 .LBB0_727
	s_mov_b64 s[20:21], 0x101f80
	s_mov_b32 m0, s50
	ds_read_b128 v[134:137], v141
	ds_read_b128 v[162:165], v142
	ds_read_b128 v[166:169], v143
	ds_read_b128 v[170:173], v144
	ds_read_b128 v[174:177], v160
	ds_read_b128 v[178:181], v160 offset:1024
	ds_read_b128 v[182:185], v160 offset:2048
	ds_read_b128 v[186:189], v160 offset:3072
	ds_read_b128 v[190:193], v160 offset:4096
	ds_read_b128 v[194:197], v160 offset:5120
	ds_read_b128 v[198:201], v160 offset:6144
	ds_read_b128 v[202:205], v160 offset:7168
	s_nop 0
	v_lshl_add_u64 v[132:133], v[132:133], 0, s[20:21]
	global_load_lds_dwordx4 v[132:133], off
	v_lshl_add_u64 v[132:133], v[132:133], 0, s[10:11]
	s_mov_b32 m0, s34
	s_nop 0
	global_load_lds_dwordx4 v[132:133], off
	s_barrier
	s_waitcnt lgkmcnt(0)
	s_setprio 1
	s_waitcnt lgkmcnt(0)
	v_mfma_f32_16x16x32_bf16 v[124:127], v[134:137], v[174:177], v[124:127]
	v_mfma_f32_16x16x32_bf16 v[120:123], v[166:169], v[174:177], v[120:123]
	v_mfma_f32_16x16x32_bf16 v[108:111], v[134:137], v[190:193], v[108:111]
	v_mfma_f32_16x16x32_bf16 v[104:107], v[166:169], v[190:193], v[104:107]
	v_mfma_f32_16x16x32_bf16 v[124:127], v[162:165], v[178:181], v[124:127]
	v_mfma_f32_16x16x32_bf16 v[120:123], v[170:173], v[178:181], v[120:123]
	v_mfma_f32_16x16x32_bf16 v[116:119], v[134:137], v[182:185], v[116:119]
	v_mfma_f32_16x16x32_bf16 v[112:115], v[166:169], v[182:185], v[112:115]
	v_mfma_f32_16x16x32_bf16 v[108:111], v[162:165], v[194:197], v[108:111]
	v_mfma_f32_16x16x32_bf16 v[104:107], v[170:173], v[194:197], v[104:107]
	v_mfma_f32_16x16x32_bf16 v[100:103], v[134:137], v[198:201], v[100:103]
	v_mfma_f32_16x16x32_bf16 v[96:99], v[166:169], v[198:201], v[96:99]
	v_mfma_f32_16x16x32_bf16 v[206:209], v[162:165], v[186:189], v[116:119]
	v_mfma_f32_16x16x32_bf16 v[210:213], v[170:173], v[186:189], v[112:115]
	v_mfma_f32_16x16x32_bf16 v[214:217], v[162:165], v[202:205], v[100:103]
	v_mfma_f32_16x16x32_bf16 v[218:221], v[170:173], v[202:205], v[96:99]
	s_setprio 0
	s_barrier
	s_nop 1
	ds_read_b128 v[96:99], v145
	ds_read_b128 v[100:103], v146
	ds_read_b128 v[112:115], v147
	ds_read_b128 v[116:119], v148
	s_barrier
	s_waitcnt lgkmcnt(0)
	s_setprio 1
	s_waitcnt lgkmcnt(0)
	v_mfma_f32_16x16x32_bf16 v[92:95], v[96:99], v[174:177], v[92:95]
	v_mfma_f32_16x16x32_bf16 v[88:91], v[112:115], v[174:177], v[88:91]
	v_mfma_f32_16x16x32_bf16 v[76:79], v[96:99], v[190:193], v[76:79]
	v_mfma_f32_16x16x32_bf16 v[72:75], v[112:115], v[190:193], v[72:75]
	v_mfma_f32_16x16x32_bf16 v[92:95], v[100:103], v[178:181], v[92:95]
	v_mfma_f32_16x16x32_bf16 v[88:91], v[116:119], v[178:181], v[88:91]
	v_mfma_f32_16x16x32_bf16 v[84:87], v[96:99], v[182:185], v[84:87]
	v_mfma_f32_16x16x32_bf16 v[80:83], v[112:115], v[182:185], v[80:83]
	v_mfma_f32_16x16x32_bf16 v[76:79], v[100:103], v[194:197], v[76:79]
	v_mfma_f32_16x16x32_bf16 v[72:75], v[116:119], v[194:197], v[72:75]
	v_mfma_f32_16x16x32_bf16 v[68:71], v[96:99], v[198:201], v[68:71]
	v_mfma_f32_16x16x32_bf16 v[64:67], v[112:115], v[198:201], v[64:67]
	v_mfma_f32_16x16x32_bf16 v[174:177], v[100:103], v[186:189], v[84:87]
	v_mfma_f32_16x16x32_bf16 v[178:181], v[116:119], v[186:189], v[80:83]
	v_mfma_f32_16x16x32_bf16 v[182:185], v[100:103], v[202:205], v[68:71]
	v_mfma_f32_16x16x32_bf16 v[186:189], v[116:119], v[202:205], v[64:67]
	s_setprio 0
	s_barrier
	s_nop 1
	ds_read_b128 v[64:67], v160 offset:16384
	ds_read_b128 v[68:71], v160 offset:17408
	ds_read_b128 v[80:83], v160 offset:18432
	ds_read_b128 v[84:87], v160 offset:19456
	ds_read_b128 v[190:193], v160 offset:20480
	ds_read_b128 v[194:197], v160 offset:21504
	ds_read_b128 v[198:201], v160 offset:22528
	ds_read_b128 v[202:205], v160 offset:23552
	s_waitcnt vmcnt(4)
	s_barrier
	s_waitcnt lgkmcnt(0)
	s_setprio 1
	s_waitcnt lgkmcnt(0)
	v_mfma_f32_16x16x32_bf16 v[60:63], v[134:137], v[64:67], v[60:63]
	v_mfma_f32_16x16x32_bf16 v[52:55], v[134:137], v[80:83], v[52:55]
	v_mfma_f32_16x16x32_bf16 v[48:51], v[166:169], v[80:83], v[48:51]
	v_mfma_f32_16x16x32_bf16 v[36:39], v[134:137], v[198:201], v[36:39]
	v_mfma_f32_16x16x32_bf16 v[32:35], v[166:169], v[198:201], v[32:35]
	v_mfma_f32_16x16x32_bf16 v[60:63], v[162:165], v[68:71], v[60:63]
	v_mfma_f32_16x16x32_bf16 v[56:59], v[166:169], v[64:67], v[56:59]
	v_mfma_f32_16x16x32_bf16 v[52:55], v[162:165], v[84:87], v[52:55]
	v_mfma_f32_16x16x32_bf16 v[48:51], v[170:173], v[84:87], v[48:51]
	v_mfma_f32_16x16x32_bf16 v[44:47], v[134:137], v[190:193], v[44:47]
	v_mfma_f32_16x16x32_bf16 v[40:43], v[166:169], v[190:193], v[40:43]
	v_mfma_f32_16x16x32_bf16 v[36:39], v[162:165], v[202:205], v[36:39]
	v_mfma_f32_16x16x32_bf16 v[32:35], v[170:173], v[202:205], v[32:35]
	v_mfma_f32_16x16x32_bf16 v[222:225], v[170:173], v[68:71], v[56:59]
	v_mfma_f32_16x16x32_bf16 v[226:229], v[162:165], v[194:197], v[44:47]
	v_mfma_f32_16x16x32_bf16 v[230:233], v[170:173], v[194:197], v[40:43]
	s_setprio 0
	s_setprio 1
	v_mfma_f32_16x16x32_bf16 v[20:23], v[96:99], v[80:83], v[20:23]
	v_mfma_f32_16x16x32_bf16 v[16:19], v[112:115], v[80:83], v[16:19]
	v_mfma_f32_16x16x32_bf16 v[12:15], v[96:99], v[190:193], v[12:15]
	v_mfma_f32_16x16x32_bf16 v[8:11], v[112:115], v[190:193], v[8:11]
	v_mfma_f32_16x16x32_bf16 v[28:31], v[96:99], v[64:67], v[28:31]
	v_mfma_f32_16x16x32_bf16 v[24:27], v[112:115], v[64:67], v[24:27]
	v_mfma_f32_16x16x32_bf16 v[20:23], v[100:103], v[84:87], v[20:23]
	v_mfma_f32_16x16x32_bf16 v[16:19], v[116:119], v[84:87], v[16:19]
	v_mfma_f32_16x16x32_bf16 v[12:15], v[100:103], v[194:197], v[12:15]
	v_mfma_f32_16x16x32_bf16 v[8:11], v[116:119], v[194:197], v[8:11]
	v_mfma_f32_16x16x32_bf16 v[4:7], v[96:99], v[198:201], v[4:7]
	v_mfma_f32_16x16x32_bf16 v[0:3], v[112:115], v[198:201], v[0:3]
	v_mfma_f32_16x16x32_bf16 v[132:135], v[100:103], v[68:71], v[28:31]
	v_mfma_f32_16x16x32_bf16 v[136:139], v[116:119], v[68:71], v[24:27]
	v_mfma_f32_16x16x32_bf16 v[162:165], v[100:103], v[202:205], v[4:7]
	v_mfma_f32_16x16x32_bf16 v[166:169], v[116:119], v[202:205], v[0:3]
	s_setprio 0
	s_barrier
	s_nop 1
	ds_read_b128 v[0:3], v149
	ds_read_b128 v[4:7], v150
	ds_read_b128 v[170:173], v151
	ds_read_b128 v[190:193], v152
	ds_read_b128 v[24:27], v160 offset:32768
	ds_read_b128 v[28:31], v160 offset:33792
	ds_read_b128 v[40:43], v160 offset:34816
	ds_read_b128 v[44:47], v160 offset:35840
	ds_read_b128 v[56:59], v160 offset:36864
	ds_read_b128 v[194:197], v160 offset:37888
	ds_read_b128 v[198:201], v160 offset:38912
	ds_read_b128 v[202:205], v160 offset:39936
	s_waitcnt vmcnt(2)
	s_barrier
	s_waitcnt lgkmcnt(0)
	s_setprio 1
	s_waitcnt lgkmcnt(0)
	v_mfma_f32_16x16x32_bf16 v[64:67], v[0:3], v[24:27], v[124:127]
	v_mfma_f32_16x16x32_bf16 v[112:115], v[4:7], v[28:31], v[64:67]
	v_mfma_f32_16x16x32_bf16 v[64:67], v[170:173], v[24:27], v[120:123]
	v_mfma_f32_16x16x32_bf16 v[116:119], v[190:193], v[28:31], v[64:67]
	v_mfma_f32_16x16x32_bf16 v[64:67], v[0:3], v[40:43], v[206:209]
	v_mfma_f32_16x16x32_bf16 v[96:99], v[4:7], v[44:47], v[64:67]
	v_mfma_f32_16x16x32_bf16 v[64:67], v[170:173], v[40:43], v[210:213]
	v_mfma_f32_16x16x32_bf16 v[100:103], v[190:193], v[44:47], v[64:67]
	v_mfma_f32_16x16x32_bf16 v[64:67], v[0:3], v[56:59], v[108:111]
	v_mfma_f32_16x16x32_bf16 v[80:83], v[4:7], v[194:197], v[64:67]
	v_mfma_f32_16x16x32_bf16 v[64:67], v[170:173], v[56:59], v[104:107]
	v_mfma_f32_16x16x32_bf16 v[84:87], v[190:193], v[194:197], v[64:67]
	v_mfma_f32_16x16x32_bf16 v[64:67], v[0:3], v[198:201], v[214:217]
	v_mfma_f32_16x16x32_bf16 v[68:71], v[170:173], v[198:201], v[218:221]
	v_mfma_f32_16x16x32_bf16 v[64:67], v[4:7], v[202:205], v[64:67]
	v_mfma_f32_16x16x32_bf16 v[68:71], v[190:193], v[202:205], v[68:71]
	s_setprio 0
	s_barrier
	ds_read_b128 v[206:209], v153
	ds_read_b128 v[210:213], v154
	ds_read_b128 v[214:217], v155
	ds_read_b128 v[218:221], v156
	s_waitcnt vmcnt(0)
	s_barrier
	s_waitcnt lgkmcnt(0)
	s_setprio 1
	s_waitcnt lgkmcnt(0)
	v_mfma_f32_16x16x32_bf16 v[92:95], v[206:209], v[24:27], v[92:95]
	v_mfma_f32_16x16x32_bf16 v[24:27], v[214:217], v[24:27], v[88:91]
	v_mfma_f32_16x16x32_bf16 v[124:127], v[218:221], v[28:31], v[24:27]
	v_mfma_f32_16x16x32_bf16 v[24:27], v[206:209], v[40:43], v[174:177]
	v_mfma_f32_16x16x32_bf16 v[104:107], v[210:213], v[44:47], v[24:27]
	v_mfma_f32_16x16x32_bf16 v[24:27], v[214:217], v[40:43], v[178:181]
	v_mfma_f32_16x16x32_bf16 v[108:111], v[218:221], v[44:47], v[24:27]
	v_mfma_f32_16x16x32_bf16 v[24:27], v[206:209], v[56:59], v[76:79]
	v_mfma_f32_16x16x32_bf16 v[88:91], v[210:213], v[194:197], v[24:27]
	v_mfma_f32_16x16x32_bf16 v[24:27], v[214:217], v[56:59], v[72:75]
	v_mfma_f32_16x16x32_bf16 v[120:123], v[210:213], v[28:31], v[92:95]
	v_mfma_f32_16x16x32_bf16 v[92:95], v[218:221], v[194:197], v[24:27]
	v_mfma_f32_16x16x32_bf16 v[24:27], v[206:209], v[198:201], v[182:185]
	v_mfma_f32_16x16x32_bf16 v[72:75], v[210:213], v[202:205], v[24:27]
	v_mfma_f32_16x16x32_bf16 v[24:27], v[214:217], v[198:201], v[186:189]
	v_mfma_f32_16x16x32_bf16 v[76:79], v[218:221], v[202:205], v[24:27]
	s_setprio 0
	s_barrier
	ds_read_b128 v[174:177], v160 offset:49152
	ds_read_b128 v[178:181], v160 offset:50176
	ds_read_b128 v[182:185], v160 offset:51200
	ds_read_b128 v[186:189], v160 offset:52224
	ds_read_b128 v[194:197], v160 offset:53248
	ds_read_b128 v[198:201], v160 offset:54272
	ds_read_b128 v[202:205], v160 offset:55296
	ds_read_b128 v[234:237], v160 offset:56320
	s_barrier
	s_waitcnt lgkmcnt(0)
	s_setprio 1
	s_waitcnt lgkmcnt(0)
	v_mfma_f32_16x16x32_bf16 v[24:27], v[0:3], v[174:177], v[60:63]
	v_mfma_f32_16x16x32_bf16 v[56:59], v[4:7], v[178:181], v[24:27]
	v_mfma_f32_16x16x32_bf16 v[24:27], v[170:173], v[174:177], v[222:225]
	v_mfma_f32_16x16x32_bf16 v[60:63], v[190:193], v[178:181], v[24:27]
	v_mfma_f32_16x16x32_bf16 v[24:27], v[0:3], v[182:185], v[52:55]
	v_mfma_f32_16x16x32_bf16 v[40:43], v[4:7], v[186:189], v[24:27]
	v_mfma_f32_16x16x32_bf16 v[24:27], v[170:173], v[182:185], v[48:51]
	v_mfma_f32_16x16x32_bf16 v[44:47], v[190:193], v[186:189], v[24:27]
	v_mfma_f32_16x16x32_bf16 v[24:27], v[0:3], v[194:197], v[226:229]
	v_mfma_f32_16x16x32_bf16 v[0:3], v[0:3], v[202:205], v[36:39]
	v_mfma_f32_16x16x32_bf16 v[24:27], v[4:7], v[198:201], v[24:27]
	v_mfma_f32_16x16x32_bf16 v[28:31], v[170:173], v[194:197], v[230:233]
	v_mfma_f32_16x16x32_bf16 v[0:3], v[4:7], v[234:237], v[0:3]
	v_mfma_f32_16x16x32_bf16 v[4:7], v[170:173], v[202:205], v[32:35]
	v_mfma_f32_16x16x32_bf16 v[28:31], v[190:193], v[198:201], v[28:31]
	v_mfma_f32_16x16x32_bf16 v[4:7], v[190:193], v[234:237], v[4:7]
	s_setprio 0
	s_setprio 1
	v_mfma_f32_16x16x32_bf16 v[32:35], v[206:209], v[174:177], v[132:135]
	v_mfma_f32_16x16x32_bf16 v[48:51], v[210:213], v[178:181], v[32:35]
	v_mfma_f32_16x16x32_bf16 v[32:35], v[214:217], v[174:177], v[136:139]
	v_mfma_f32_16x16x32_bf16 v[20:23], v[206:209], v[182:185], v[20:23]
	v_mfma_f32_16x16x32_bf16 v[16:19], v[214:217], v[182:185], v[16:19]
	v_mfma_f32_16x16x32_bf16 v[12:15], v[206:209], v[194:197], v[12:15]
	v_mfma_f32_16x16x32_bf16 v[8:11], v[214:217], v[194:197], v[8:11]
	v_mfma_f32_16x16x32_bf16 v[52:55], v[218:221], v[178:181], v[32:35]
	v_mfma_f32_16x16x32_bf16 v[32:35], v[210:213], v[186:189], v[20:23]
	v_mfma_f32_16x16x32_bf16 v[36:39], v[218:221], v[186:189], v[16:19]
	v_mfma_f32_16x16x32_bf16 v[16:19], v[210:213], v[198:201], v[12:15]
	v_mfma_f32_16x16x32_bf16 v[20:23], v[218:221], v[198:201], v[8:11]
	v_mfma_f32_16x16x32_bf16 v[8:11], v[206:209], v[202:205], v[162:165]
	v_mfma_f32_16x16x32_bf16 v[12:15], v[214:217], v[202:205], v[166:169]
	v_mfma_f32_16x16x32_bf16 v[8:11], v[210:213], v[234:237], v[8:11]
	v_mfma_f32_16x16x32_bf16 v[12:15], v[218:221], v[234:237], v[12:15]
	s_setprio 0
	s_barrier
	s_and_saveexec_b64 s[20:21], s[4:5]
	s_cbranch_execz .LBB0_730
	s_barrier

.LBB0_784:
	ds_read_b128 v[136:139], v141
	ds_read_b128 v[162:165], v142
	ds_read_b128 v[166:169], v143
	ds_read_b128 v[170:173], v144
	s_add_u32 s40, s18, 0xffffff00
	s_addc_u32 s41, s19, -1
	s_mov_b32 m0, s34
	ds_read_b128 v[174:177], v160
	ds_read_b128 v[178:181], v160 offset:1024
	ds_read_b128 v[182:185], v160 offset:2048
	ds_read_b128 v[186:189], v160 offset:3072
	ds_read_b128 v[190:193], v160 offset:4096
	ds_read_b128 v[194:197], v160 offset:5120
	ds_read_b128 v[198:201], v160 offset:6144
	ds_read_b128 v[202:205], v160 offset:7168
	v_lshl_add_u64 v[206:207], v[132:133], 0, s[40:41]
	global_load_lds_dwordx4 v[206:207], off
	v_lshl_add_u64 v[206:207], v[206:207], 0, s[4:5]
	s_mov_b32 m0, s24
	s_nop 0
	global_load_lds_dwordx4 v[206:207], off
	s_waitcnt lgkmcnt(8)
	s_barrier
	s_waitcnt lgkmcnt(0)
	v_mfma_f32_16x16x32_bf16 v[124:127], v[136:139], v[174:177], v[124:127]
	v_mfma_f32_16x16x32_bf16 v[120:123], v[166:169], v[174:177], v[120:123]
	v_mfma_f32_16x16x32_bf16 v[116:119], v[136:139], v[182:185], v[116:119]
	v_mfma_f32_16x16x32_bf16 v[112:115], v[166:169], v[182:185], v[112:115]
	v_mfma_f32_16x16x32_bf16 v[108:111], v[136:139], v[190:193], v[108:111]
	v_mfma_f32_16x16x32_bf16 v[104:107], v[166:169], v[190:193], v[104:107]
	v_mfma_f32_16x16x32_bf16 v[100:103], v[136:139], v[198:201], v[100:103]
	v_mfma_f32_16x16x32_bf16 v[96:99], v[166:169], v[198:201], v[96:99]
	v_mfma_f32_16x16x32_bf16 v[124:127], v[162:165], v[178:181], v[124:127]
	v_mfma_f32_16x16x32_bf16 v[120:123], v[170:173], v[178:181], v[120:123]
	v_mfma_f32_16x16x32_bf16 v[116:119], v[162:165], v[186:189], v[116:119]
	v_mfma_f32_16x16x32_bf16 v[112:115], v[170:173], v[186:189], v[112:115]
	v_mfma_f32_16x16x32_bf16 v[108:111], v[162:165], v[194:197], v[108:111]
	v_mfma_f32_16x16x32_bf16 v[104:107], v[170:173], v[194:197], v[104:107]
	v_mfma_f32_16x16x32_bf16 v[100:103], v[162:165], v[202:205], v[100:103]
	v_mfma_f32_16x16x32_bf16 v[96:99], v[170:173], v[202:205], v[96:99]
	s_barrier
	s_add_u32 s40, s18, 0xffbfff80
	s_addc_u32 s41, s19, -1
	s_mov_b64 s[42:43], s[40:41]
	s_mov_b32 m0, s27
	ds_read_b128 v[206:209], v145
	ds_read_b128 v[210:213], v146
	ds_read_b128 v[214:217], v147
	ds_read_b128 v[218:221], v148
	v_lshl_add_u64 v[222:223], v[134:135], 0, s[42:43]
	global_load_lds_dwordx4 v[222:223], off
	v_lshl_add_u64 v[222:223], v[222:223], 0, s[4:5]
	s_mov_b32 m0, s28
	s_nop 0
	global_load_lds_dwordx4 v[222:223], off
	s_barrier
	s_waitcnt lgkmcnt(0)
	v_mfma_f32_16x16x32_bf16 v[92:95], v[206:209], v[174:177], v[92:95]
	v_mfma_f32_16x16x32_bf16 v[88:91], v[214:217], v[174:177], v[88:91]
	v_mfma_f32_16x16x32_bf16 v[84:87], v[206:209], v[182:185], v[84:87]
	v_mfma_f32_16x16x32_bf16 v[80:83], v[214:217], v[182:185], v[80:83]
	v_mfma_f32_16x16x32_bf16 v[76:79], v[206:209], v[190:193], v[76:79]
	v_mfma_f32_16x16x32_bf16 v[72:75], v[214:217], v[190:193], v[72:75]
	v_mfma_f32_16x16x32_bf16 v[68:71], v[206:209], v[198:201], v[68:71]
	v_mfma_f32_16x16x32_bf16 v[64:67], v[214:217], v[198:201], v[64:67]
	v_mfma_f32_16x16x32_bf16 v[92:95], v[210:213], v[178:181], v[92:95]
	v_mfma_f32_16x16x32_bf16 v[88:91], v[218:221], v[178:181], v[88:91]
	v_mfma_f32_16x16x32_bf16 v[84:87], v[210:213], v[186:189], v[84:87]
	v_mfma_f32_16x16x32_bf16 v[80:83], v[218:221], v[186:189], v[80:83]
	v_mfma_f32_16x16x32_bf16 v[76:79], v[210:213], v[194:197], v[76:79]
	v_mfma_f32_16x16x32_bf16 v[72:75], v[218:221], v[194:197], v[72:75]
	v_mfma_f32_16x16x32_bf16 v[68:71], v[210:213], v[202:205], v[68:71]
	v_mfma_f32_16x16x32_bf16 v[64:67], v[218:221], v[202:205], v[64:67]
	s_mov_b32 m0, s15
	s_barrier
	ds_read_b128 v[174:177], v160 offset:16384
	ds_read_b128 v[178:181], v160 offset:17408
	ds_read_b128 v[182:185], v160 offset:18432
	ds_read_b128 v[186:189], v160 offset:19456
	ds_read_b128 v[190:193], v160 offset:20480
	ds_read_b128 v[194:197], v160 offset:21504
	ds_read_b128 v[198:201], v160 offset:22528
	ds_read_b128 v[202:205], v160 offset:23552
	v_lshl_add_u64 v[222:223], v[132:133], 0, s[40:41]
	global_load_lds_dwordx4 v[222:223], off
	v_lshl_add_u64 v[222:223], v[222:223], 0, s[4:5]
	s_mov_b32 m0, s35
	s_nop 0
	global_load_lds_dwordx4 v[222:223], off
	s_barrier
	s_waitcnt lgkmcnt(0)
	v_mfma_f32_16x16x32_bf16 v[60:63], v[136:139], v[174:177], v[60:63]
	v_mfma_f32_16x16x32_bf16 v[56:59], v[166:169], v[174:177], v[56:59]
	v_mfma_f32_16x16x32_bf16 v[52:55], v[136:139], v[182:185], v[52:55]
	v_mfma_f32_16x16x32_bf16 v[48:51], v[166:169], v[182:185], v[48:51]
	v_mfma_f32_16x16x32_bf16 v[44:47], v[136:139], v[190:193], v[44:47]
	v_mfma_f32_16x16x32_bf16 v[40:43], v[166:169], v[190:193], v[40:43]
	v_mfma_f32_16x16x32_bf16 v[36:39], v[136:139], v[198:201], v[36:39]
	v_mfma_f32_16x16x32_bf16 v[32:35], v[166:169], v[198:201], v[32:35]
	v_mfma_f32_16x16x32_bf16 v[60:63], v[162:165], v[178:181], v[60:63]
	v_mfma_f32_16x16x32_bf16 v[56:59], v[170:173], v[178:181], v[56:59]
	v_mfma_f32_16x16x32_bf16 v[52:55], v[162:165], v[186:189], v[52:55]
	v_mfma_f32_16x16x32_bf16 v[48:51], v[170:173], v[186:189], v[48:51]
	v_mfma_f32_16x16x32_bf16 v[44:47], v[162:165], v[194:197], v[44:47]
	v_mfma_f32_16x16x32_bf16 v[40:43], v[170:173], v[194:197], v[40:43]
	v_mfma_f32_16x16x32_bf16 v[36:39], v[162:165], v[202:205], v[36:39]
	v_mfma_f32_16x16x32_bf16 v[32:35], v[170:173], v[202:205], v[32:35]
	s_barrier
	s_add_u32 s40, s18, 0xffffff80
	s_addc_u32 s41, s19, -1
	s_mov_b64 s[42:43], s[40:41]
	s_mov_b32 m0, s29
	v_lshl_add_u64 v[136:137], v[134:135], 0, s[42:43]
	global_load_lds_dwordx4 v[136:137], off
	v_lshl_add_u64 v[136:137], v[136:137], 0, s[4:5]
	s_mov_b32 m0, s30
	s_nop 0
	global_load_lds_dwordx4 v[136:137], off
	s_waitcnt vmcnt(6)
	s_barrier
	v_mfma_f32_16x16x32_bf16 v[28:31], v[206:209], v[174:177], v[28:31]
	v_mfma_f32_16x16x32_bf16 v[24:27], v[214:217], v[174:177], v[24:27]
	v_mfma_f32_16x16x32_bf16 v[20:23], v[206:209], v[182:185], v[20:23]
	v_mfma_f32_16x16x32_bf16 v[16:19], v[214:217], v[182:185], v[16:19]
	v_mfma_f32_16x16x32_bf16 v[12:15], v[206:209], v[190:193], v[12:15]
	v_mfma_f32_16x16x32_bf16 v[8:11], v[214:217], v[190:193], v[8:11]
	v_mfma_f32_16x16x32_bf16 v[4:7], v[206:209], v[198:201], v[4:7]
	v_mfma_f32_16x16x32_bf16 v[0:3], v[214:217], v[198:201], v[0:3]
	v_mfma_f32_16x16x32_bf16 v[28:31], v[210:213], v[178:181], v[28:31]
	v_mfma_f32_16x16x32_bf16 v[24:27], v[218:221], v[178:181], v[24:27]
	v_mfma_f32_16x16x32_bf16 v[20:23], v[210:213], v[186:189], v[20:23]
	v_mfma_f32_16x16x32_bf16 v[16:19], v[218:221], v[186:189], v[16:19]
	v_mfma_f32_16x16x32_bf16 v[12:15], v[210:213], v[194:197], v[12:15]
	v_mfma_f32_16x16x32_bf16 v[8:11], v[218:221], v[194:197], v[8:11]
	v_mfma_f32_16x16x32_bf16 v[4:7], v[210:213], v[202:205], v[4:7]
	v_mfma_f32_16x16x32_bf16 v[0:3], v[218:221], v[202:205], v[0:3]
	s_barrier
	ds_read_b128 v[136:139], v149
	ds_read_b128 v[162:165], v150
	ds_read_b128 v[166:169], v151
	ds_read_b128 v[170:173], v152
	s_mov_b32 m0, s36
	ds_read_b128 v[174:177], v160 offset:32768
	ds_read_b128 v[178:181], v160 offset:33792
	ds_read_b128 v[182:185], v160 offset:34816
	ds_read_b128 v[186:189], v160 offset:35840
	ds_read_b128 v[190:193], v160 offset:36864
	ds_read_b128 v[194:197], v160 offset:37888
	ds_read_b128 v[198:201], v160 offset:38912
	ds_read_b128 v[202:205], v160 offset:39936
	v_lshl_add_u64 v[206:207], v[132:133], 0, s[40:41]
	global_load_lds_dwordx4 v[206:207], off
	v_lshl_add_u64 v[206:207], v[206:207], 0, s[4:5]
	s_mov_b32 m0, s37
	s_nop 0
	global_load_lds_dwordx4 v[206:207], off
	s_waitcnt lgkmcnt(8)
	s_barrier
	s_waitcnt lgkmcnt(0)
	v_mfma_f32_16x16x32_bf16 v[124:127], v[136:139], v[174:177], v[124:127]
	v_mfma_f32_16x16x32_bf16 v[120:123], v[166:169], v[174:177], v[120:123]
	v_mfma_f32_16x16x32_bf16 v[116:119], v[136:139], v[182:185], v[116:119]
	v_mfma_f32_16x16x32_bf16 v[112:115], v[166:169], v[182:185], v[112:115]
	v_mfma_f32_16x16x32_bf16 v[108:111], v[136:139], v[190:193], v[108:111]
	v_mfma_f32_16x16x32_bf16 v[104:107], v[166:169], v[190:193], v[104:107]
	v_mfma_f32_16x16x32_bf16 v[100:103], v[136:139], v[198:201], v[100:103]
	v_mfma_f32_16x16x32_bf16 v[96:99], v[166:169], v[198:201], v[96:99]
	v_mfma_f32_16x16x32_bf16 v[124:127], v[162:165], v[178:181], v[124:127]
	v_mfma_f32_16x16x32_bf16 v[120:123], v[170:173], v[178:181], v[120:123]
	v_mfma_f32_16x16x32_bf16 v[116:119], v[162:165], v[186:189], v[116:119]
	v_mfma_f32_16x16x32_bf16 v[112:115], v[170:173], v[186:189], v[112:115]
	v_mfma_f32_16x16x32_bf16 v[108:111], v[162:165], v[194:197], v[108:111]
	v_mfma_f32_16x16x32_bf16 v[104:107], v[170:173], v[194:197], v[104:107]
	v_mfma_f32_16x16x32_bf16 v[100:103], v[162:165], v[202:205], v[100:103]
	v_mfma_f32_16x16x32_bf16 v[96:99], v[170:173], v[202:205], v[96:99]
	s_barrier
	s_add_u32 s40, s18, 0xffc00000
	s_addc_u32 s41, s19, -1
	s_mov_b64 s[42:43], s[40:41]
	s_mov_b32 m0, s17
	ds_read_b128 v[206:209], v153
	ds_read_b128 v[210:213], v154
	ds_read_b128 v[214:217], v155
	ds_read_b128 v[218:221], v156
	v_lshl_add_u64 v[222:223], v[134:135], 0, s[42:43]
	global_load_lds_dwordx4 v[222:223], off
	v_lshl_add_u64 v[222:223], v[222:223], 0, s[4:5]
	s_mov_b32 m0, s21
	s_nop 0
	global_load_lds_dwordx4 v[222:223], off
	s_barrier
	s_waitcnt lgkmcnt(0)
	v_mfma_f32_16x16x32_bf16 v[92:95], v[206:209], v[174:177], v[92:95]
	v_mfma_f32_16x16x32_bf16 v[88:91], v[214:217], v[174:177], v[88:91]
	v_mfma_f32_16x16x32_bf16 v[84:87], v[206:209], v[182:185], v[84:87]
	v_mfma_f32_16x16x32_bf16 v[80:83], v[214:217], v[182:185], v[80:83]
	v_mfma_f32_16x16x32_bf16 v[76:79], v[206:209], v[190:193], v[76:79]
	v_mfma_f32_16x16x32_bf16 v[72:75], v[214:217], v[190:193], v[72:75]
	v_mfma_f32_16x16x32_bf16 v[68:71], v[206:209], v[198:201], v[68:71]
	v_mfma_f32_16x16x32_bf16 v[64:67], v[214:217], v[198:201], v[64:67]
	v_mfma_f32_16x16x32_bf16 v[92:95], v[210:213], v[178:181], v[92:95]
	v_mfma_f32_16x16x32_bf16 v[88:91], v[218:221], v[178:181], v[88:91]
	v_mfma_f32_16x16x32_bf16 v[84:87], v[210:213], v[186:189], v[84:87]
	v_mfma_f32_16x16x32_bf16 v[80:83], v[218:221], v[186:189], v[80:83]
	v_mfma_f32_16x16x32_bf16 v[76:79], v[210:213], v[194:197], v[76:79]
	v_mfma_f32_16x16x32_bf16 v[72:75], v[218:221], v[194:197], v[72:75]
	v_mfma_f32_16x16x32_bf16 v[68:71], v[210:213], v[202:205], v[68:71]
	v_mfma_f32_16x16x32_bf16 v[64:67], v[218:221], v[202:205], v[64:67]
	s_mov_b32 m0, s22
	s_barrier
	ds_read_b128 v[174:177], v160 offset:49152
	ds_read_b128 v[178:181], v160 offset:50176
	ds_read_b128 v[182:185], v160 offset:51200
	ds_read_b128 v[186:189], v160 offset:52224
	ds_read_b128 v[190:193], v160 offset:53248
	ds_read_b128 v[194:197], v160 offset:54272
	ds_read_b128 v[198:201], v160 offset:55296
	ds_read_b128 v[202:205], v160 offset:56320
	v_lshl_add_u64 v[222:223], v[132:133], 0, s[40:41]
	global_load_lds_dwordx4 v[222:223], off
	v_lshl_add_u64 v[222:223], v[222:223], 0, s[4:5]
	s_mov_b32 m0, s23
	s_nop 0
	global_load_lds_dwordx4 v[222:223], off
	s_barrier
	s_waitcnt lgkmcnt(0)
	v_mfma_f32_16x16x32_bf16 v[60:63], v[136:139], v[174:177], v[60:63]
	v_mfma_f32_16x16x32_bf16 v[56:59], v[166:169], v[174:177], v[56:59]
	v_mfma_f32_16x16x32_bf16 v[52:55], v[136:139], v[182:185], v[52:55]
	v_mfma_f32_16x16x32_bf16 v[48:51], v[166:169], v[182:185], v[48:51]
	v_mfma_f32_16x16x32_bf16 v[44:47], v[136:139], v[190:193], v[44:47]
	v_mfma_f32_16x16x32_bf16 v[40:43], v[166:169], v[190:193], v[40:43]
	v_mfma_f32_16x16x32_bf16 v[36:39], v[136:139], v[198:201], v[36:39]
	v_mfma_f32_16x16x32_bf16 v[32:35], v[166:169], v[198:201], v[32:35]
	v_mfma_f32_16x16x32_bf16 v[60:63], v[162:165], v[178:181], v[60:63]
	v_mfma_f32_16x16x32_bf16 v[56:59], v[170:173], v[178:181], v[56:59]
	v_mfma_f32_16x16x32_bf16 v[52:55], v[162:165], v[186:189], v[52:55]
	v_mfma_f32_16x16x32_bf16 v[48:51], v[170:173], v[186:189], v[48:51]
	v_mfma_f32_16x16x32_bf16 v[44:47], v[162:165], v[194:197], v[44:47]
	v_mfma_f32_16x16x32_bf16 v[40:43], v[170:173], v[194:197], v[40:43]
	v_mfma_f32_16x16x32_bf16 v[36:39], v[162:165], v[202:205], v[36:39]
	v_mfma_f32_16x16x32_bf16 v[32:35], v[170:173], v[202:205], v[32:35]
	s_barrier
	s_mov_b64 s[40:41], s[18:19]
	s_mov_b32 m0, s25
	v_lshl_add_u64 v[136:137], v[134:135], 0, s[40:41]
	global_load_lds_dwordx4 v[136:137], off
	v_lshl_add_u64 v[136:137], v[136:137], 0, s[4:5]
	s_mov_b32 m0, s26
	s_nop 0
	global_load_lds_dwordx4 v[136:137], off
	s_waitcnt vmcnt(6)
	s_barrier
	v_mfma_f32_16x16x32_bf16 v[28:31], v[206:209], v[174:177], v[28:31]
	v_mfma_f32_16x16x32_bf16 v[24:27], v[214:217], v[174:177], v[24:27]
	v_mfma_f32_16x16x32_bf16 v[20:23], v[206:209], v[182:185], v[20:23]
	v_mfma_f32_16x16x32_bf16 v[16:19], v[214:217], v[182:185], v[16:19]
	v_mfma_f32_16x16x32_bf16 v[12:15], v[206:209], v[190:193], v[12:15]
	v_mfma_f32_16x16x32_bf16 v[8:11], v[214:217], v[190:193], v[8:11]
	v_mfma_f32_16x16x32_bf16 v[4:7], v[206:209], v[198:201], v[4:7]
	v_mfma_f32_16x16x32_bf16 v[0:3], v[214:217], v[198:201], v[0:3]
	v_mfma_f32_16x16x32_bf16 v[28:31], v[210:213], v[178:181], v[28:31]
	v_mfma_f32_16x16x32_bf16 v[24:27], v[218:221], v[178:181], v[24:27]
	v_mfma_f32_16x16x32_bf16 v[20:23], v[210:213], v[186:189], v[20:23]
	v_mfma_f32_16x16x32_bf16 v[16:19], v[218:221], v[186:189], v[16:19]
	v_mfma_f32_16x16x32_bf16 v[12:15], v[210:213], v[194:197], v[12:15]
	v_mfma_f32_16x16x32_bf16 v[8:11], v[218:221], v[194:197], v[8:11]
	v_mfma_f32_16x16x32_bf16 v[4:7], v[210:213], v[202:205], v[4:7]
	v_mfma_f32_16x16x32_bf16 v[0:3], v[218:221], v[202:205], v[0:3]
	s_add_i32 s31, s31, 2
	s_add_u32 s18, s18, 0x100
	s_addc_u32 s19, s19, 0
	s_cmpk_lt_u32 s31, 0xfc
	s_barrier
	s_cbranch_scc1 .LBB0_784
	s_mov_b64 s[18:19], 0x407f80
	s_mov_b32 m0, s34
	ds_read_b128 v[134:137], v141
	ds_read_b128 v[162:165], v142
	ds_read_b128 v[166:169], v143
	ds_read_b128 v[170:173], v144
	ds_read_b128 v[174:177], v160
	ds_read_b128 v[178:181], v160 offset:1024
	ds_read_b128 v[182:185], v160 offset:2048
	ds_read_b128 v[186:189], v160 offset:3072
	ds_read_b128 v[190:193], v160 offset:4096
	ds_read_b128 v[194:197], v160 offset:5120
	ds_read_b128 v[198:201], v160 offset:6144
	ds_read_b128 v[202:205], v160 offset:7168
	s_nop 0
	v_lshl_add_u64 v[132:133], v[132:133], 0, s[18:19]
	global_load_lds_dwordx4 v[132:133], off
	v_lshl_add_u64 v[132:133], v[132:133], 0, s[4:5]
	s_mov_b32 m0, s24
	s_nop 0
	global_load_lds_dwordx4 v[132:133], off
	s_barrier
	s_waitcnt lgkmcnt(0)
	s_setprio 1
	s_waitcnt lgkmcnt(0)
	v_mfma_f32_16x16x32_bf16 v[124:127], v[134:137], v[174:177], v[124:127]
	v_mfma_f32_16x16x32_bf16 v[120:123], v[166:169], v[174:177], v[120:123]
	v_mfma_f32_16x16x32_bf16 v[116:119], v[134:137], v[182:185], v[116:119]
	v_mfma_f32_16x16x32_bf16 v[112:115], v[166:169], v[182:185], v[112:115]
	v_mfma_f32_16x16x32_bf16 v[100:103], v[134:137], v[198:201], v[100:103]
	v_mfma_f32_16x16x32_bf16 v[96:99], v[166:169], v[198:201], v[96:99]
	v_mfma_f32_16x16x32_bf16 v[124:127], v[162:165], v[178:181], v[124:127]
	v_mfma_f32_16x16x32_bf16 v[120:123], v[170:173], v[178:181], v[120:123]
	v_mfma_f32_16x16x32_bf16 v[116:119], v[162:165], v[186:189], v[116:119]
	v_mfma_f32_16x16x32_bf16 v[112:115], v[170:173], v[186:189], v[112:115]
	v_mfma_f32_16x16x32_bf16 v[108:111], v[134:137], v[190:193], v[108:111]
	v_mfma_f32_16x16x32_bf16 v[104:107], v[166:169], v[190:193], v[104:107]
	v_mfma_f32_16x16x32_bf16 v[100:103], v[162:165], v[202:205], v[100:103]
	v_mfma_f32_16x16x32_bf16 v[96:99], v[170:173], v[202:205], v[96:99]
	v_mfma_f32_16x16x32_bf16 v[206:209], v[162:165], v[194:197], v[108:111]
	v_mfma_f32_16x16x32_bf16 v[210:213], v[170:173], v[194:197], v[104:107]
	s_setprio 0
	s_barrier
	s_nop 1
	ds_read_b128 v[104:107], v145
	ds_read_b128 v[108:111], v146
	ds_read_b128 v[214:217], v147
	ds_read_b128 v[218:221], v148
	s_barrier
	s_waitcnt lgkmcnt(0)
	s_setprio 1
	s_waitcnt lgkmcnt(0)
	v_mfma_f32_16x16x32_bf16 v[84:87], v[104:107], v[182:185], v[84:87]
	v_mfma_f32_16x16x32_bf16 v[80:83], v[214:217], v[182:185], v[80:83]
	v_mfma_f32_16x16x32_bf16 v[68:71], v[104:107], v[198:201], v[68:71]
	v_mfma_f32_16x16x32_bf16 v[64:67], v[214:217], v[198:201], v[64:67]
	v_mfma_f32_16x16x32_bf16 v[92:95], v[104:107], v[174:177], v[92:95]
	v_mfma_f32_16x16x32_bf16 v[88:91], v[214:217], v[174:177], v[88:91]
	v_mfma_f32_16x16x32_bf16 v[84:87], v[108:111], v[186:189], v[84:87]
	v_mfma_f32_16x16x32_bf16 v[80:83], v[218:221], v[186:189], v[80:83]
	v_mfma_f32_16x16x32_bf16 v[76:79], v[104:107], v[190:193], v[76:79]
	v_mfma_f32_16x16x32_bf16 v[72:75], v[214:217], v[190:193], v[72:75]
	v_mfma_f32_16x16x32_bf16 v[68:71], v[108:111], v[202:205], v[68:71]
	v_mfma_f32_16x16x32_bf16 v[64:67], v[218:221], v[202:205], v[64:67]
	v_mfma_f32_16x16x32_bf16 v[222:225], v[108:111], v[178:181], v[92:95]
	v_mfma_f32_16x16x32_bf16 v[174:177], v[218:221], v[178:181], v[88:91]
	v_mfma_f32_16x16x32_bf16 v[178:181], v[108:111], v[194:197], v[76:79]
	v_mfma_f32_16x16x32_bf16 v[182:185], v[218:221], v[194:197], v[72:75]
	s_setprio 0
	s_barrier
	s_nop 0
	ds_read_b128 v[72:75], v160 offset:16384
	ds_read_b128 v[76:79], v160 offset:17408
	ds_read_b128 v[88:91], v160 offset:18432
	ds_read_b128 v[92:95], v160 offset:19456
	ds_read_b128 v[186:189], v160 offset:20480
	ds_read_b128 v[190:193], v160 offset:21504
	ds_read_b128 v[194:197], v160 offset:22528
	ds_read_b128 v[198:201], v160 offset:23552
	s_waitcnt vmcnt(4)
	s_barrier
	s_waitcnt lgkmcnt(0)
	s_setprio 1
	s_waitcnt lgkmcnt(0)
	v_mfma_f32_16x16x32_bf16 v[60:63], v[134:137], v[72:75], v[60:63]
	v_mfma_f32_16x16x32_bf16 v[56:59], v[166:169], v[72:75], v[56:59]
	v_mfma_f32_16x16x32_bf16 v[52:55], v[134:137], v[88:91], v[52:55]
	v_mfma_f32_16x16x32_bf16 v[48:51], v[166:169], v[88:91], v[48:51]
	v_mfma_f32_16x16x32_bf16 v[36:39], v[134:137], v[194:197], v[36:39]
	v_mfma_f32_16x16x32_bf16 v[32:35], v[166:169], v[194:197], v[32:35]
	v_mfma_f32_16x16x32_bf16 v[60:63], v[162:165], v[76:79], v[60:63]
	v_mfma_f32_16x16x32_bf16 v[56:59], v[170:173], v[76:79], v[56:59]
	v_mfma_f32_16x16x32_bf16 v[52:55], v[162:165], v[92:95], v[52:55]
	v_mfma_f32_16x16x32_bf16 v[48:51], v[170:173], v[92:95], v[48:51]
	v_mfma_f32_16x16x32_bf16 v[44:47], v[134:137], v[186:189], v[44:47]
	v_mfma_f32_16x16x32_bf16 v[40:43], v[166:169], v[186:189], v[40:43]
	v_mfma_f32_16x16x32_bf16 v[36:39], v[162:165], v[198:201], v[36:39]
	v_mfma_f32_16x16x32_bf16 v[32:35], v[170:173], v[198:201], v[32:35]
	v_mfma_f32_16x16x32_bf16 v[202:205], v[162:165], v[190:193], v[44:47]
	v_mfma_f32_16x16x32_bf16 v[226:229], v[170:173], v[190:193], v[40:43]
	s_setprio 0
	s_setprio 1
	v_mfma_f32_16x16x32_bf16 v[20:23], v[104:107], v[88:91], v[20:23]
	v_mfma_f32_16x16x32_bf16 v[16:19], v[214:217], v[88:91], v[16:19]
	v_mfma_f32_16x16x32_bf16 v[4:7], v[104:107], v[194:197], v[4:7]
	v_mfma_f32_16x16x32_bf16 v[0:3], v[214:217], v[194:197], v[0:3]
	v_mfma_f32_16x16x32_bf16 v[28:31], v[104:107], v[72:75], v[28:31]
	v_mfma_f32_16x16x32_bf16 v[24:27], v[214:217], v[72:75], v[24:27]
	v_mfma_f32_16x16x32_bf16 v[20:23], v[108:111], v[92:95], v[20:23]
	v_mfma_f32_16x16x32_bf16 v[16:19], v[218:221], v[92:95], v[16:19]
	v_mfma_f32_16x16x32_bf16 v[12:15], v[104:107], v[186:189], v[12:15]
	v_mfma_f32_16x16x32_bf16 v[8:11], v[214:217], v[186:189], v[8:11]
	v_mfma_f32_16x16x32_bf16 v[4:7], v[108:111], v[198:201], v[4:7]
	v_mfma_f32_16x16x32_bf16 v[0:3], v[218:221], v[198:201], v[0:3]
	v_mfma_f32_16x16x32_bf16 v[132:135], v[108:111], v[76:79], v[28:31]
	v_mfma_f32_16x16x32_bf16 v[136:139], v[218:221], v[76:79], v[24:27]
	v_mfma_f32_16x16x32_bf16 v[162:165], v[108:111], v[190:193], v[12:15]
	v_mfma_f32_16x16x32_bf16 v[166:169], v[218:221], v[190:193], v[8:11]
	s_setprio 0
	s_barrier
	s_nop 0
	ds_read_b128 v[8:11], v149
	ds_read_b128 v[12:15], v150
	ds_read_b128 v[170:173], v151
	ds_read_b128 v[186:189], v152
	ds_read_b128 v[24:27], v160 offset:32768
	ds_read_b128 v[28:31], v160 offset:33792
	ds_read_b128 v[40:43], v160 offset:34816
	ds_read_b128 v[44:47], v160 offset:35840
	ds_read_b128 v[190:193], v160 offset:36864
	ds_read_b128 v[194:197], v160 offset:37888
	ds_read_b128 v[198:201], v160 offset:38912
	ds_read_b128 v[214:217], v160 offset:39936
	s_waitcnt vmcnt(2)
	s_barrier
	s_waitcnt lgkmcnt(0)
	s_setprio 1
	s_waitcnt lgkmcnt(0)
	v_mfma_f32_16x16x32_bf16 v[72:75], v[8:11], v[24:27], v[124:127]
	v_mfma_f32_16x16x32_bf16 v[124:127], v[12:15], v[28:31], v[72:75]
	v_mfma_f32_16x16x32_bf16 v[72:75], v[170:173], v[24:27], v[120:123]
	v_mfma_f32_16x16x32_bf16 v[120:123], v[186:189], v[28:31], v[72:75]
	v_mfma_f32_16x16x32_bf16 v[72:75], v[8:11], v[40:43], v[116:119]
	v_mfma_f32_16x16x32_bf16 v[108:111], v[12:15], v[44:47], v[72:75]
	v_mfma_f32_16x16x32_bf16 v[72:75], v[170:173], v[40:43], v[112:115]
	v_mfma_f32_16x16x32_bf16 v[104:107], v[186:189], v[44:47], v[72:75]
	v_mfma_f32_16x16x32_bf16 v[72:75], v[8:11], v[190:193], v[206:209]
	v_mfma_f32_16x16x32_bf16 v[92:95], v[12:15], v[194:197], v[72:75]
	v_mfma_f32_16x16x32_bf16 v[72:75], v[170:173], v[190:193], v[210:213]
	v_mfma_f32_16x16x32_bf16 v[88:91], v[186:189], v[194:197], v[72:75]
	v_mfma_f32_16x16x32_bf16 v[72:75], v[8:11], v[198:201], v[100:103]
	v_mfma_f32_16x16x32_bf16 v[76:79], v[12:15], v[214:217], v[72:75]
	v_mfma_f32_16x16x32_bf16 v[72:75], v[170:173], v[198:201], v[96:99]
	v_mfma_f32_16x16x32_bf16 v[72:75], v[186:189], v[214:217], v[72:75]
	s_setprio 0
	s_barrier
	ds_read_b128 v[206:209], v153
	ds_read_b128 v[210:213], v154
	ds_read_b128 v[218:221], v155
	ds_read_b128 v[230:233], v156
	s_waitcnt vmcnt(0)
	s_barrier
	s_waitcnt lgkmcnt(0)
	s_setprio 1
	s_waitcnt lgkmcnt(0)
	v_mfma_f32_16x16x32_bf16 v[96:99], v[206:209], v[24:27], v[222:225]
	v_mfma_f32_16x16x32_bf16 v[24:27], v[218:221], v[24:27], v[174:177]
	v_mfma_f32_16x16x32_bf16 v[112:115], v[230:233], v[28:31], v[24:27]
	v_mfma_f32_16x16x32_bf16 v[24:27], v[206:209], v[40:43], v[84:87]
	v_mfma_f32_16x16x32_bf16 v[100:103], v[210:213], v[44:47], v[24:27]
	v_mfma_f32_16x16x32_bf16 v[24:27], v[218:221], v[40:43], v[80:83]
	v_mfma_f32_16x16x32_bf16 v[116:119], v[210:213], v[28:31], v[96:99]
	v_mfma_f32_16x16x32_bf16 v[96:99], v[230:233], v[44:47], v[24:27]
	v_mfma_f32_16x16x32_bf16 v[24:27], v[206:209], v[190:193], v[178:181]
	v_mfma_f32_16x16x32_bf16 v[84:87], v[210:213], v[194:197], v[24:27]
	v_mfma_f32_16x16x32_bf16 v[24:27], v[218:221], v[190:193], v[182:185]
	v_mfma_f32_16x16x32_bf16 v[80:83], v[230:233], v[194:197], v[24:27]
	v_mfma_f32_16x16x32_bf16 v[24:27], v[206:209], v[198:201], v[68:71]
	v_mfma_f32_16x16x32_bf16 v[68:71], v[210:213], v[214:217], v[24:27]
	v_mfma_f32_16x16x32_bf16 v[24:27], v[218:221], v[198:201], v[64:67]
	v_mfma_f32_16x16x32_bf16 v[64:67], v[230:233], v[214:217], v[24:27]
	s_setprio 0
	s_barrier
	ds_read_b128 v[174:177], v160 offset:49152
	ds_read_b128 v[178:181], v160 offset:50176
	ds_read_b128 v[182:185], v160 offset:51200
	ds_read_b128 v[190:193], v160 offset:52224
	ds_read_b128 v[194:197], v160 offset:53248
	ds_read_b128 v[198:201], v160 offset:54272
	ds_read_b128 v[214:217], v160 offset:55296
	ds_read_b128 v[222:225], v160 offset:56320
	s_barrier
	s_waitcnt lgkmcnt(0)
	s_setprio 1
	s_waitcnt lgkmcnt(0)
	v_mfma_f32_16x16x32_bf16 v[24:27], v[8:11], v[174:177], v[60:63]
	v_mfma_f32_16x16x32_bf16 v[60:63], v[12:15], v[178:181], v[24:27]
	v_mfma_f32_16x16x32_bf16 v[24:27], v[170:173], v[174:177], v[56:59]
	v_mfma_f32_16x16x32_bf16 v[56:59], v[186:189], v[178:181], v[24:27]
	v_mfma_f32_16x16x32_bf16 v[24:27], v[8:11], v[182:185], v[52:55]
	v_mfma_f32_16x16x32_bf16 v[44:47], v[12:15], v[190:193], v[24:27]
	v_mfma_f32_16x16x32_bf16 v[24:27], v[170:173], v[182:185], v[48:51]
	v_mfma_f32_16x16x32_bf16 v[40:43], v[186:189], v[190:193], v[24:27]
	v_mfma_f32_16x16x32_bf16 v[24:27], v[8:11], v[194:197], v[202:205]
	v_mfma_f32_16x16x32_bf16 v[8:11], v[8:11], v[214:217], v[36:39]
	v_mfma_f32_16x16x32_bf16 v[28:31], v[12:15], v[198:201], v[24:27]
	v_mfma_f32_16x16x32_bf16 v[24:27], v[170:173], v[194:197], v[226:229]
	v_mfma_f32_16x16x32_bf16 v[12:15], v[12:15], v[222:225], v[8:11]
	v_mfma_f32_16x16x32_bf16 v[8:11], v[170:173], v[214:217], v[32:35]
	v_mfma_f32_16x16x32_bf16 v[24:27], v[186:189], v[198:201], v[24:27]
	v_mfma_f32_16x16x32_bf16 v[8:11], v[186:189], v[222:225], v[8:11]
	s_setprio 0
	s_setprio 1
	v_mfma_f32_16x16x32_bf16 v[32:35], v[206:209], v[174:177], v[132:135]
	v_mfma_f32_16x16x32_bf16 v[52:55], v[210:213], v[178:181], v[32:35]
	v_mfma_f32_16x16x32_bf16 v[32:35], v[218:221], v[174:177], v[136:139]
	v_mfma_f32_16x16x32_bf16 v[16:19], v[218:221], v[182:185], v[16:19]
	v_mfma_f32_16x16x32_bf16 v[48:51], v[230:233], v[178:181], v[32:35]
	v_mfma_f32_16x16x32_bf16 v[20:23], v[206:209], v[182:185], v[20:23]
	v_mfma_f32_16x16x32_bf16 v[32:35], v[230:233], v[190:193], v[16:19]
	v_mfma_f32_16x16x32_bf16 v[16:19], v[206:209], v[194:197], v[162:165]
	v_mfma_f32_16x16x32_bf16 v[36:39], v[210:213], v[190:193], v[20:23]
	v_mfma_f32_16x16x32_bf16 v[20:23], v[210:213], v[198:201], v[16:19]
	v_mfma_f32_16x16x32_bf16 v[16:19], v[218:221], v[194:197], v[166:169]
	v_mfma_f32_16x16x32_bf16 v[4:7], v[206:209], v[214:217], v[4:7]
	v_mfma_f32_16x16x32_bf16 v[0:3], v[218:221], v[214:217], v[0:3]
	v_mfma_f32_16x16x32_bf16 v[16:19], v[230:233], v[198:201], v[16:19]
	v_mfma_f32_16x16x32_bf16 v[4:7], v[210:213], v[222:225], v[4:7]
	v_mfma_f32_16x16x32_bf16 v[0:3], v[230:233], v[222:225], v[0:3]
	s_setprio 0
	s_barrier
	s_and_saveexec_b64 s[18:19], s[2:3]
	s_cbranch_execz .LBB0_787
	s_barrier
